# diff-attention finalize: per-row reloads of the 4 sub-LN gains (with vmcnt(0) drains) replaced by one preload per unit; on top of SwiGLU epilogue rewrite
# speedup vs baseline: 1.0058x; 1.0058x over previous
; __device__ __forceinline__ unsigned cvtpk(float lo, float hi) { unsigned r; asm volatile("v_cvt_pk_bf16_f32 %0, %1, %2" : "=v"(r) : "v"(lo), "v"(hi)); return r; }
; __device__ __forceinline__ float sx(float v, int mask, int lane) { return __int_as_float(__builtin_amdgcn_ds_bpermute((lane ^ mask) << 2, __float_as_int(v))); }
; __device__ __forceinline__ int crow(int r, int hi) { return (r & 3) + 8 * (r >> 2) + 4 * hi; }
;     __device__ __forceinline__ long qtok(int wid, int i) const { return (long)b * T + res + dil * (qs0 + 32 * wid + i); }
;     __device__ __forceinline__ long qtok(int wid, int i) const { return (long)b * T + 256 * qb + 32 * wid + i; }
;     __device__ __forceinline__ long qtok(int wid, int i) const { return (long)b * T + 128 * qb + 32 * (wid & 3) + i; }
; template <class Pol>
; __device__ __forceinline__ void attn_unit(const Pol& P, LAS unsigned char* lds, const Ptrs& X, bf16x8& pq0, bf16x8& pq1, bf16x8& pq2, bf16x8& pq3, bf16x8& pk_, bf16x8& pv_, bool have, const Pol& Pn, bool hasn) {
;     ...
;         if (wid < 4) {
; #pragma unroll
;             for (int r = 0; r < 16; ++r) { const int row = 32 * wid + crow(r, hi); float s = 0.f;
; #pragma unroll
;                 for (int d = 0; d < NB; ++d) { const float y = o[d][r] * rli[r] - XB[row * 128 + d * 32 + r32]; o[d][r] = y; s += y * y; }
;                 s += sx(s, 1, lane); s += sx(s, 2, lane); s += sx(s, 4, lane); s += sx(s, 8, lane); s += sx(s, 16, lane);
;                 const float rs = (1.0f - LAM_INIT) / sqrtf(s * (1.0f / 128.f) + SUBLN_EPS);
;                 const long tok = P.qtok(wid, crow(r, hi));
; #pragma unroll
;                 for (int d = 0; d < NB; ++d) X.att[tok * D + P.h * 128 + d * 32 + r32] = (bf16_t)(cvtpk(o[d][r] * rs * X.subln[d * 32 + r32], 0.f) & 0xffffu); }
;         }
.LBB0_297:
	s_cmp_gt_i32 s2, 3
	v_mov_b64_e32 v[242:243], v[218:219]
	s_waitcnt lgkmcnt(0)
	s_barrier
	s_cbranch_scc1 .LBB0_299
	s_lshl_b32 s0, s2, 14
	s_add_i32 s0, s0, 0
	s_add_i32 s0, s0, 0x11000
	v_lshlrev_b32_e32 v4, 2, v204
	v_add_u32_e32 v11, s0, v4
	v_lshlrev_b32_e32 v2, 2, v230
	v_lshl_add_u32 v154, v229, 11, v11
	v_xor_b32_e32 v10, 4, v2
	v_xor_b32_e32 v9, 8, v2
	v_xor_b32_e32 v8, 16, v2
	v_xor_b32_e32 v7, 32, v2
	v_xor_b32_e32 v6, 64, v2
	ds_read2_b32 v[2:3], v154 offset1:32
	v_mov_b32_e32 v157, 0x3727c5ac
	s_mov_b32 s2, 0xf800000
	s_mov_b32 s3, 0x3f24fd5c
	v_readlane_b32 s6, v254, 27
	s_waitcnt lgkmcnt(0)
	v_fma_f32 v155, v112, v0, -v2
	v_fma_f32 v128, v128, v0, -v3
	ds_read2_b32 v[2:3], v154 offset0:64 offset1:96
	v_mul_f32_e32 v112, v128, v128
	v_fmac_f32_e32 v112, v155, v155
	v_readlane_b32 s7, v254, 28
	s_nop 4
	global_load_dword v206, v4, s[6:7]
	global_load_dword v207, v4, s[6:7] offset:128
	global_load_dword v208, v4, s[6:7] offset:256
	global_load_dword v209, v4, s[6:7] offset:384
	s_lshl_b32 s26, s40, 1
	s_waitcnt lgkmcnt(0)
	v_fma_f32 v96, v96, v0, -v2
	v_fmac_f32_e32 v112, v96, v96
	v_fma_f32 v80, v80, v0, -v3
	v_fmac_f32_e32 v112, v80, v80
	ds_bpermute_b32 v0, v10, v112
	s_waitcnt lgkmcnt(0)
	v_add_f32_e32 v0, v112, v0
	ds_bpermute_b32 v2, v9, v0
	s_waitcnt lgkmcnt(0)
	v_add_f32_e32 v0, v0, v2
	ds_bpermute_b32 v2, v8, v0
	s_waitcnt lgkmcnt(0)
	v_add_f32_e32 v0, v0, v2
	ds_bpermute_b32 v2, v7, v0
	s_waitcnt lgkmcnt(0)
	v_add_f32_e32 v0, v0, v2
	ds_bpermute_b32 v2, v6, v0
	s_waitcnt lgkmcnt(0)
	v_add_f32_e32 v0, v0, v2
	v_fmamk_f32 v0, v0, 0x3c000000, v157
	v_cmp_gt_f32_e32 vcc, s2, v0
	v_mul_f32_e32 v2, 0x4f800000, v0
	s_nop 0
	v_cndmask_b32_e32 v0, v0, v2, vcc
	v_sqrt_f32_e32 v2, v0
	s_nop 0
	v_add_u32_e32 v3, -1, v2
	v_fma_f32 v112, -v3, v2, v0
	v_cmp_ge_f32_e64 s[4:5], 0, v112
	v_add_u32_e32 v112, 1, v2
	s_nop 0
	v_cndmask_b32_e64 v3, v2, v3, s[4:5]
	v_fma_f32 v2, -v112, v2, v0
	v_cmp_lt_f32_e64 s[4:5], 0, v2
	s_nop 1
	v_cndmask_b32_e64 v2, v3, v112, s[4:5]
	v_mul_f32_e32 v3, 0x37800000, v2
	v_cndmask_b32_e32 v2, v2, v3, vcc
	v_cmp_class_f32_e32 vcc, v0, v216
	s_nop 1
	v_cndmask_b32_e32 v0, v2, v0, vcc
	v_div_scale_f32 v2, s[0:1], v0, v0, s3
	v_rcp_f32_e32 v3, v2
	s_nop 0
	v_fma_f32 v112, -v2, v3, 1.0
	v_fmac_f32_e32 v3, v112, v3
	v_div_scale_f32 v112, vcc, s3, v0, s3
	v_mul_f32_e32 v154, v112, v3
	v_fma_f32 v156, -v2, v154, v112
	v_fmac_f32_e32 v154, v156, v3
	v_fma_f32 v2, -v2, v154, v112
	v_div_fmas_f32 v2, v2, v3, v154
	s_waitcnt vmcnt(0)
	v_mov_b32_e32 v154, v206
	v_div_fixup_f32 v112, v2, v0, s3
	v_or_b32_e32 v0, s20, v228
	v_or_b32_e32 v0, s31, v0
	v_lshlrev_b64 v[2:3], 11, v[0:1]
	v_mul_f32_e32 v0, v155, v112
	v_lshl_add_u64 v[2:3], s[90:91], 0, v[2:3]
	v_lshl_add_u64 v[2:3], v[2:3], 0, s[26:27]
	v_mul_f32_e32 v128, v128, v112
	v_mul_f32_e32 v96, v96, v112
	v_mul_f32_e32 v80, v80, v112
	v_or_b32_e32 v112, 1, v228
	s_nop 0
	v_mul_f32_e32 v0, v154, v0
	v_cvt_pk_bf16_f32 v154, v0, v1
	v_lshlrev_b32_e32 v0, 1, v204
	v_lshl_add_u64 v[2:3], v[2:3], 0, v[0:1]
	global_store_short v[2:3], v154, off
	v_mov_b32_e32 v154, v207
	s_nop 0
	v_mul_f32_e32 v128, v154, v128
	v_cvt_pk_bf16_f32 v128, v128, v1
	global_store_short v[2:3], v128, off offset:64
	v_mov_b32_e32 v128, v208
	s_nop 0
	v_mul_f32_e32 v96, v128, v96
	v_cvt_pk_bf16_f32 v96, v96, v1
	global_store_short v[2:3], v96, off offset:128
	v_mov_b32_e32 v96, v209
	s_nop 0
	v_mul_f32_e32 v80, v80, v96
	v_cvt_pk_bf16_f32 v80, v80, v1
	global_store_short v[2:3], v80, off offset:192
	v_lshl_add_u32 v80, v112, 9, v11
	ds_read2_b32 v[2:3], v80 offset1:32
	s_waitcnt lgkmcnt(0)
	v_fma_f32 v113, v113, v153, -v2
	v_fma_f32 v128, v129, v153, -v3
	ds_read2_b32 v[2:3], v80 offset0:64 offset1:96
	v_mul_f32_e32 v129, v128, v128
	v_fmac_f32_e32 v129, v113, v113
	s_waitcnt lgkmcnt(0)
	v_fma_f32 v96, v97, v153, -v2
	v_fmac_f32_e32 v129, v96, v96
	v_fma_f32 v80, v81, v153, -v3
	v_fmac_f32_e32 v129, v80, v80
	ds_bpermute_b32 v2, v10, v129
	s_waitcnt lgkmcnt(0)
	v_add_f32_e32 v2, v129, v2
	ds_bpermute_b32 v3, v9, v2
	s_waitcnt lgkmcnt(0)
	v_add_f32_e32 v2, v2, v3
	ds_bpermute_b32 v3, v8, v2
	s_waitcnt lgkmcnt(0)
	v_add_f32_e32 v2, v2, v3
	ds_bpermute_b32 v3, v7, v2
	s_waitcnt lgkmcnt(0)
	v_add_f32_e32 v2, v2, v3
	ds_bpermute_b32 v3, v6, v2
	s_waitcnt lgkmcnt(0)
	v_add_f32_e32 v2, v2, v3
	v_fmamk_f32 v2, v2, 0x3c000000, v157
	v_cmp_gt_f32_e32 vcc, s2, v2
	v_mul_f32_e32 v3, 0x4f800000, v2
	s_nop 0
	v_cndmask_b32_e32 v2, v2, v3, vcc
	v_sqrt_f32_e32 v3, v2
	s_nop 0
	v_add_u32_e32 v81, -1, v3
	v_fma_f32 v97, -v81, v3, v2
	v_cmp_ge_f32_e64 s[4:5], 0, v97
	v_add_u32_e32 v97, 1, v3
	s_nop 0
	v_cndmask_b32_e64 v81, v3, v81, s[4:5]
	v_fma_f32 v3, -v97, v3, v2
	v_cmp_lt_f32_e64 s[4:5], 0, v3
	s_nop 1
	v_cndmask_b32_e64 v3, v81, v97, s[4:5]
	v_mul_f32_e32 v81, 0x37800000, v3
	v_cndmask_b32_e32 v3, v3, v81, vcc
	v_cmp_class_f32_e32 vcc, v2, v216
	s_nop 1
	v_cndmask_b32_e32 v2, v3, v2, vcc
	v_div_scale_f32 v3, s[0:1], v2, v2, s3
	v_rcp_f32_e32 v81, v3
	s_nop 0
	v_fma_f32 v97, -v3, v81, 1.0
	v_fmac_f32_e32 v81, v97, v81
	v_div_scale_f32 v97, vcc, s3, v2, s3
	v_mul_f32_e32 v129, v97, v81
	v_fma_f32 v153, -v3, v129, v97
	v_fmac_f32_e32 v129, v153, v81
	v_fma_f32 v3, -v3, v129, v97
	v_div_fmas_f32 v3, v3, v81, v129
	v_div_fixup_f32 v81, v3, v2, s3
	v_or_b32_e32 v2, s20, v112
	v_mov_b32_e32 v112, v206
	v_mul_f32_e32 v97, v113, v81
	v_or_b32_e32 v2, s31, v2
	v_mov_b32_e32 v3, v1
	v_lshlrev_b64 v[2:3], 11, v[2:3]
	v_lshl_add_u64 v[2:3], s[90:91], 0, v[2:3]
	v_lshl_add_u64 v[2:3], v[2:3], 0, s[26:27]
	v_lshl_add_u64 v[2:3], v[2:3], 0, v[0:1]
	v_mul_f32_e32 v96, v96, v81
	v_mul_f32_e32 v80, v80, v81
	s_nop 0
	v_mul_f32_e32 v97, v112, v97
	v_cvt_pk_bf16_f32 v97, v97, v1
	v_mov_b32_e32 v112, v207
	s_nop 0
	global_store_short v[2:3], v97, off
	v_mul_f32_e32 v97, v128, v81
	s_nop 0
	v_mul_f32_e32 v97, v112, v97
	v_cvt_pk_bf16_f32 v97, v97, v1
	global_store_short v[2:3], v97, off offset:64
	v_mov_b32_e32 v97, v208
	s_nop 0
	v_mul_f32_e32 v96, v97, v96
	v_cvt_pk_bf16_f32 v96, v96, v1
	v_mov_b32_e32 v81, v209
	s_nop 0
	v_mul_f32_e32 v80, v80, v81
	global_store_short v[2:3], v96, off offset:128
	v_cvt_pk_bf16_f32 v80, v80, v1
	v_or_b32_e32 v96, 2, v228
	global_store_short v[2:3], v80, off offset:192
	v_lshl_add_u32 v80, v96, 9, v11
	ds_read2_b32 v[2:3], v80 offset1:32
	s_waitcnt lgkmcnt(0)
; __device__ __forceinline__ unsigned cvtpk(float lo, float hi) { unsigned r; asm volatile("v_cvt_pk_bf16_f32 %0, %1, %2" : "=v"(r) : "v"(lo), "v"(hi)); return r; }
; __device__ __forceinline__ float sx(float v, int mask, int lane) { return __int_as_float(__builtin_amdgcn_ds_bpermute((lane ^ mask) << 2, __float_as_int(v))); }
; __device__ __forceinline__ int crow(int r, int hi) { return (r & 3) + 8 * (r >> 2) + 4 * hi; }
;     __device__ __forceinline__ long qtok(int wid, int i) const { return (long)b * T + res + dil * (qs0 + 32 * wid + i); }
;     __device__ __forceinline__ long qtok(int wid, int i) const { return (long)b * T + 256 * qb + 32 * wid + i; }
;     __device__ __forceinline__ long qtok(int wid, int i) const { return (long)b * T + 128 * qb + 32 * (wid & 3) + i; }
; template <class Pol>
; __device__ __forceinline__ void attn_unit(const Pol& P, LAS unsigned char* lds, const Ptrs& X, bf16x8& pq0, bf16x8& pq1, bf16x8& pq2, bf16x8& pq3, bf16x8& pk_, bf16x8& pv_, bool have, const Pol& Pn, bool hasn) {
;     ...
;         if (wid < 4) {
; #pragma unroll
;             for (int r = 0; r < 16; ++r) { const int row = 32 * wid + crow(r, hi); float s = 0.f;
; #pragma unroll
;                 for (int d = 0; d < NB; ++d) { const float y = o[d][r] * rli[r] - XB[row * 128 + d * 32 + r32]; o[d][r] = y; s += y * y; }
;                 s += sx(s, 1, lane); s += sx(s, 2, lane); s += sx(s, 4, lane); s += sx(s, 8, lane); s += sx(s, 16, lane);
;                 const float rs = (1.0f - LAM_INIT) / sqrtf(s * (1.0f / 128.f) + SUBLN_EPS);
;                 const long tok = P.qtok(wid, crow(r, hi));
; #pragma unroll
;                 for (int d = 0; d < NB; ++d) X.att[tok * D + P.h * 128 + d * 32 + r32] = (bf16_t)(cvtpk(o[d][r] * rs * X.subln[d * 32 + r32], 0.f) & 0xffffu); }
;         }
	v_fma_f32 v97, v114, v152, -v2
	v_fma_f32 v112, v130, v152, -v3
	ds_read2_b32 v[2:3], v80 offset0:64 offset1:96
	v_mul_f32_e32 v113, v112, v112
	v_fmac_f32_e32 v113, v97, v97
	s_waitcnt lgkmcnt(0)
	v_fma_f32 v81, v98, v152, -v2
	v_fmac_f32_e32 v113, v81, v81
	v_fma_f32 v80, v82, v152, -v3
	v_fmac_f32_e32 v113, v80, v80
	ds_bpermute_b32 v2, v10, v113
	s_waitcnt lgkmcnt(0)
	v_add_f32_e32 v2, v113, v2
	ds_bpermute_b32 v3, v9, v2
	s_waitcnt lgkmcnt(0)
	v_add_f32_e32 v2, v2, v3
	ds_bpermute_b32 v3, v8, v2
	s_waitcnt lgkmcnt(0)
	v_add_f32_e32 v2, v2, v3
	ds_bpermute_b32 v3, v7, v2
	s_waitcnt lgkmcnt(0)
	v_add_f32_e32 v2, v2, v3
	ds_bpermute_b32 v3, v6, v2
	s_waitcnt lgkmcnt(0)
	v_add_f32_e32 v2, v2, v3
	v_fmamk_f32 v2, v2, 0x3c000000, v157
	v_cmp_gt_f32_e32 vcc, s2, v2
	v_mul_f32_e32 v3, 0x4f800000, v2
	s_nop 0
	v_cndmask_b32_e32 v2, v2, v3, vcc
	v_sqrt_f32_e32 v3, v2
	s_nop 0
	v_add_u32_e32 v82, -1, v3
	v_fma_f32 v98, -v82, v3, v2
	v_cmp_ge_f32_e64 s[4:5], 0, v98
	v_add_u32_e32 v98, 1, v3
	s_nop 0
	v_cndmask_b32_e64 v82, v3, v82, s[4:5]
	v_fma_f32 v3, -v98, v3, v2
	v_cmp_lt_f32_e64 s[4:5], 0, v3
	s_nop 1
	v_cndmask_b32_e64 v3, v82, v98, s[4:5]
	v_mul_f32_e32 v82, 0x37800000, v3
	v_cndmask_b32_e32 v3, v3, v82, vcc
	v_cmp_class_f32_e32 vcc, v2, v216
	s_nop 1
	v_cndmask_b32_e32 v2, v3, v2, vcc
	v_div_scale_f32 v3, s[0:1], v2, v2, s3
	v_rcp_f32_e32 v82, v3
	s_nop 0
	v_fma_f32 v98, -v3, v82, 1.0
	v_fmac_f32_e32 v82, v98, v82
	v_div_scale_f32 v98, vcc, s3, v2, s3
	v_mul_f32_e32 v113, v98, v82
	v_fma_f32 v114, -v3, v113, v98
	v_fmac_f32_e32 v113, v114, v82
	v_fma_f32 v3, -v3, v113, v98
	v_div_fmas_f32 v3, v3, v82, v113
	v_div_fixup_f32 v82, v3, v2, s3
	v_or_b32_e32 v2, s20, v96
	v_mul_f32_e32 v96, v97, v82
	v_mov_b32_e32 v97, v206
	v_or_b32_e32 v2, s31, v2
	v_mov_b32_e32 v3, v1
	v_lshlrev_b64 v[2:3], 11, v[2:3]
	v_lshl_add_u64 v[2:3], s[90:91], 0, v[2:3]
	v_lshl_add_u64 v[2:3], v[2:3], 0, s[26:27]
	v_lshl_add_u64 v[2:3], v[2:3], 0, v[0:1]
	v_mul_f32_e32 v81, v81, v82
	v_mul_f32_e32 v80, v80, v82
	s_nop 0
	v_mul_f32_e32 v96, v97, v96
	v_cvt_pk_bf16_f32 v96, v96, v1
	v_mov_b32_e32 v97, v207
	s_nop 0
	global_store_short v[2:3], v96, off
	v_mul_f32_e32 v96, v112, v82
	s_nop 0
	v_mul_f32_e32 v96, v97, v96
	v_cvt_pk_bf16_f32 v96, v96, v1
	global_store_short v[2:3], v96, off offset:64
	v_mov_b32_e32 v96, v208
	s_nop 0
	v_mul_f32_e32 v81, v96, v81
	v_cvt_pk_bf16_f32 v81, v81, v1
	global_store_short v[2:3], v81, off offset:128
	v_mov_b32_e32 v81, v209
	v_or_b32_e32 v96, 3, v228
	s_nop 0
	v_mul_f32_e32 v80, v80, v81
	v_cvt_pk_bf16_f32 v80, v80, v1
	global_store_short v[2:3], v80, off offset:192
	v_lshl_add_u32 v80, v96, 9, v11
	ds_read2_b32 v[2:3], v80 offset1:32
	s_waitcnt lgkmcnt(0)
	v_fma_f32 v97, v115, v151, -v2
	v_fma_f32 v98, v131, v151, -v3
	ds_read2_b32 v[2:3], v80 offset0:64 offset1:96
	v_mul_f32_e32 v82, v98, v98
	v_fmac_f32_e32 v82, v97, v97
	s_waitcnt lgkmcnt(0)
	v_fma_f32 v81, v99, v151, -v2
	v_fmac_f32_e32 v82, v81, v81
	v_fma_f32 v80, v83, v151, -v3
	v_fmac_f32_e32 v82, v80, v80
	ds_bpermute_b32 v2, v10, v82
	s_waitcnt lgkmcnt(0)
	v_add_f32_e32 v2, v82, v2
	ds_bpermute_b32 v3, v9, v2
	s_waitcnt lgkmcnt(0)
	v_add_f32_e32 v2, v2, v3
	ds_bpermute_b32 v3, v8, v2
	s_waitcnt lgkmcnt(0)
	v_add_f32_e32 v2, v2, v3
	ds_bpermute_b32 v3, v7, v2
	s_waitcnt lgkmcnt(0)
	v_add_f32_e32 v2, v2, v3
	ds_bpermute_b32 v3, v6, v2
	s_waitcnt lgkmcnt(0)
	v_add_f32_e32 v2, v2, v3
	v_fmamk_f32 v2, v2, 0x3c000000, v157
	v_cmp_gt_f32_e32 vcc, s2, v2
	v_mul_f32_e32 v3, 0x4f800000, v2
	s_nop 0
	v_cndmask_b32_e32 v2, v2, v3, vcc
	v_sqrt_f32_e32 v3, v2
	s_nop 0
	v_add_u32_e32 v82, -1, v3
	v_fma_f32 v83, -v82, v3, v2
	v_cmp_ge_f32_e64 s[4:5], 0, v83
	v_add_u32_e32 v83, 1, v3
	s_nop 0
	v_cndmask_b32_e64 v82, v3, v82, s[4:5]
	v_fma_f32 v3, -v83, v3, v2
	v_cmp_lt_f32_e64 s[4:5], 0, v3
	s_nop 1
	v_cndmask_b32_e64 v3, v82, v83, s[4:5]
	v_mul_f32_e32 v82, 0x37800000, v3
	v_cndmask_b32_e32 v3, v3, v82, vcc
	v_cmp_class_f32_e32 vcc, v2, v216
	s_nop 1
	v_cndmask_b32_e32 v2, v3, v2, vcc
	v_div_scale_f32 v3, s[0:1], v2, v2, s3
	v_rcp_f32_e32 v82, v3
	s_nop 0
	v_fma_f32 v83, -v3, v82, 1.0
	v_fmac_f32_e32 v82, v83, v82
	v_div_scale_f32 v83, vcc, s3, v2, s3
	v_mul_f32_e32 v99, v83, v82
	v_fma_f32 v112, -v3, v99, v83
	v_fmac_f32_e32 v99, v112, v82
	v_fma_f32 v3, -v3, v99, v83
	v_div_fmas_f32 v3, v3, v82, v99
	v_div_fixup_f32 v82, v3, v2, s3
	v_or_b32_e32 v2, s20, v96
	v_mov_b32_e32 v96, v206
	v_mul_f32_e32 v83, v97, v82
	v_or_b32_e32 v2, s31, v2
	v_mov_b32_e32 v3, v1
	v_lshlrev_b64 v[2:3], 11, v[2:3]
	v_lshl_add_u64 v[2:3], s[90:91], 0, v[2:3]
	v_lshl_add_u64 v[2:3], v[2:3], 0, s[26:27]
	v_lshl_add_u64 v[2:3], v[2:3], 0, v[0:1]
	v_mul_f32_e32 v81, v81, v82
	v_mul_f32_e32 v80, v80, v82
	s_nop 0
	v_mul_f32_e32 v83, v96, v83
	v_cvt_pk_bf16_f32 v83, v83, v1
	v_mov_b32_e32 v96, v207
	s_nop 0
	global_store_short v[2:3], v83, off
	v_mul_f32_e32 v83, v98, v82
	s_nop 0
	v_mul_f32_e32 v83, v96, v83
	v_cvt_pk_bf16_f32 v83, v83, v1
	global_store_short v[2:3], v83, off offset:64
	v_mov_b32_e32 v83, v208
	s_nop 0
	v_mul_f32_e32 v81, v83, v81
	v_cvt_pk_bf16_f32 v81, v81, v1
	global_store_short v[2:3], v81, off offset:128
	v_mov_b32_e32 v81, v209
	v_or_b32_e32 v83, 8, v228
	s_nop 0
	v_mul_f32_e32 v80, v80, v81
	v_cvt_pk_bf16_f32 v80, v80, v1
	global_store_short v[2:3], v80, off offset:192
	v_lshl_add_u32 v80, v83, 9, v11
	ds_read2_b32 v[2:3], v80 offset1:32
	s_waitcnt lgkmcnt(0)
	v_fma_f32 v96, v116, v150, -v2
	v_fma_f32 v97, v132, v150, -v3
	ds_read2_b32 v[2:3], v80 offset0:64 offset1:96
	v_mul_f32_e32 v82, v97, v97
	v_fmac_f32_e32 v82, v96, v96
	s_waitcnt lgkmcnt(0)
; __device__ __forceinline__ unsigned cvtpk(float lo, float hi) { unsigned r; asm volatile("v_cvt_pk_bf16_f32 %0, %1, %2" : "=v"(r) : "v"(lo), "v"(hi)); return r; }
; __device__ __forceinline__ float sx(float v, int mask, int lane) { return __int_as_float(__builtin_amdgcn_ds_bpermute((lane ^ mask) << 2, __float_as_int(v))); }
; __device__ __forceinline__ int crow(int r, int hi) { return (r & 3) + 8 * (r >> 2) + 4 * hi; }
;     __device__ __forceinline__ long qtok(int wid, int i) const { return (long)b * T + res + dil * (qs0 + 32 * wid + i); }
;     __device__ __forceinline__ long qtok(int wid, int i) const { return (long)b * T + 256 * qb + 32 * wid + i; }
;     __device__ __forceinline__ long qtok(int wid, int i) const { return (long)b * T + 128 * qb + 32 * (wid & 3) + i; }
; template <class Pol>
; __device__ __forceinline__ void attn_unit(const Pol& P, LAS unsigned char* lds, const Ptrs& X, bf16x8& pq0, bf16x8& pq1, bf16x8& pq2, bf16x8& pq3, bf16x8& pk_, bf16x8& pv_, bool have, const Pol& Pn, bool hasn) {
;     ...
;         if (wid < 4) {
; #pragma unroll
;             for (int r = 0; r < 16; ++r) { const int row = 32 * wid + crow(r, hi); float s = 0.f;
; #pragma unroll
;                 for (int d = 0; d < NB; ++d) { const float y = o[d][r] * rli[r] - XB[row * 128 + d * 32 + r32]; o[d][r] = y; s += y * y; }
;                 s += sx(s, 1, lane); s += sx(s, 2, lane); s += sx(s, 4, lane); s += sx(s, 8, lane); s += sx(s, 16, lane);
;                 const float rs = (1.0f - LAM_INIT) / sqrtf(s * (1.0f / 128.f) + SUBLN_EPS);
;                 const long tok = P.qtok(wid, crow(r, hi));
; #pragma unroll
;                 for (int d = 0; d < NB; ++d) X.att[tok * D + P.h * 128 + d * 32 + r32] = (bf16_t)(cvtpk(o[d][r] * rs * X.subln[d * 32 + r32], 0.f) & 0xffffu); }
;         }
	v_fma_f32 v81, v100, v150, -v2
	v_fmac_f32_e32 v82, v81, v81
	v_fma_f32 v80, v84, v150, -v3
	v_fmac_f32_e32 v82, v80, v80
	ds_bpermute_b32 v2, v10, v82
	s_waitcnt lgkmcnt(0)
	v_add_f32_e32 v2, v82, v2
	ds_bpermute_b32 v3, v9, v2
	s_waitcnt lgkmcnt(0)
	v_add_f32_e32 v2, v2, v3
	ds_bpermute_b32 v3, v8, v2
	s_waitcnt lgkmcnt(0)
	v_add_f32_e32 v2, v2, v3
	ds_bpermute_b32 v3, v7, v2
	s_waitcnt lgkmcnt(0)
	v_add_f32_e32 v2, v2, v3
	ds_bpermute_b32 v3, v6, v2
	s_waitcnt lgkmcnt(0)
	v_add_f32_e32 v2, v2, v3
	v_fmamk_f32 v2, v2, 0x3c000000, v157
	v_cmp_gt_f32_e32 vcc, s2, v2
	v_mul_f32_e32 v3, 0x4f800000, v2
	s_nop 0
	v_cndmask_b32_e32 v2, v2, v3, vcc
	v_sqrt_f32_e32 v3, v2
	s_nop 0
	v_add_u32_e32 v82, -1, v3
	v_fma_f32 v84, -v82, v3, v2
	v_cmp_ge_f32_e64 s[4:5], 0, v84
	v_add_u32_e32 v84, 1, v3
	s_nop 0
	v_cndmask_b32_e64 v82, v3, v82, s[4:5]
	v_fma_f32 v3, -v84, v3, v2
	v_cmp_lt_f32_e64 s[4:5], 0, v3
	s_nop 1
	v_cndmask_b32_e64 v3, v82, v84, s[4:5]
	v_mul_f32_e32 v82, 0x37800000, v3
	v_cndmask_b32_e32 v3, v3, v82, vcc
	v_cmp_class_f32_e32 vcc, v2, v216
	s_nop 1
	v_cndmask_b32_e32 v2, v3, v2, vcc
	v_div_scale_f32 v3, s[0:1], v2, v2, s3
	v_rcp_f32_e32 v82, v3
	s_nop 0
	v_fma_f32 v84, -v3, v82, 1.0
	v_fmac_f32_e32 v82, v84, v82
	v_div_scale_f32 v84, vcc, s3, v2, s3
	v_mul_f32_e32 v98, v84, v82
	v_fma_f32 v99, -v3, v98, v84
	v_fmac_f32_e32 v98, v99, v82
	v_fma_f32 v3, -v3, v98, v84
	v_mov_b32_e32 v84, v206
	v_div_fmas_f32 v3, v3, v82, v98
	v_div_fixup_f32 v82, v3, v2, s3
	v_or_b32_e32 v2, s20, v83
	v_mul_f32_e32 v83, v96, v82
	v_or_b32_e32 v2, s31, v2
	v_mov_b32_e32 v3, v1
	v_lshlrev_b64 v[2:3], 11, v[2:3]
	v_lshl_add_u64 v[2:3], s[90:91], 0, v[2:3]
	v_lshl_add_u64 v[2:3], v[2:3], 0, s[26:27]
	v_lshl_add_u64 v[2:3], v[2:3], 0, v[0:1]
	v_mul_f32_e32 v81, v81, v82
	v_mul_f32_e32 v80, v80, v82
	s_nop 0
	v_mul_f32_e32 v83, v84, v83
	v_cvt_pk_bf16_f32 v83, v83, v1
	v_mov_b32_e32 v84, v207
	s_nop 0
	global_store_short v[2:3], v83, off
	v_mul_f32_e32 v83, v97, v82
	s_nop 0
	v_mul_f32_e32 v83, v84, v83
	v_cvt_pk_bf16_f32 v83, v83, v1
	global_store_short v[2:3], v83, off offset:64
	v_mov_b32_e32 v83, v208
	s_nop 0
	v_mul_f32_e32 v81, v83, v81
	v_cvt_pk_bf16_f32 v81, v81, v1
	global_store_short v[2:3], v81, off offset:128
	v_mov_b32_e32 v81, v209
	v_or_b32_e32 v83, 9, v228
	s_nop 0
	v_mul_f32_e32 v80, v80, v81
	v_cvt_pk_bf16_f32 v80, v80, v1
	global_store_short v[2:3], v80, off offset:192
	v_lshl_add_u32 v80, v83, 9, v11
	ds_read2_b32 v[2:3], v80 offset1:32
	s_waitcnt lgkmcnt(0)
	v_fma_f32 v84, v117, v149, -v2
	v_fma_f32 v96, v133, v149, -v3
	ds_read2_b32 v[2:3], v80 offset0:64 offset1:96
	v_mul_f32_e32 v82, v96, v96
	v_fmac_f32_e32 v82, v84, v84
	s_waitcnt lgkmcnt(0)
	v_fma_f32 v81, v101, v149, -v2
	v_fmac_f32_e32 v82, v81, v81
	v_fma_f32 v80, v85, v149, -v3
	v_fmac_f32_e32 v82, v80, v80
	ds_bpermute_b32 v2, v10, v82
	s_waitcnt lgkmcnt(0)
	v_add_f32_e32 v2, v82, v2
	ds_bpermute_b32 v3, v9, v2
	s_waitcnt lgkmcnt(0)
	v_add_f32_e32 v2, v2, v3
	ds_bpermute_b32 v3, v8, v2
	s_waitcnt lgkmcnt(0)
	v_add_f32_e32 v2, v2, v3
	ds_bpermute_b32 v3, v7, v2
	s_waitcnt lgkmcnt(0)
	v_add_f32_e32 v2, v2, v3
	ds_bpermute_b32 v3, v6, v2
	s_waitcnt lgkmcnt(0)
	v_add_f32_e32 v2, v2, v3
	v_fmamk_f32 v2, v2, 0x3c000000, v157
	v_cmp_gt_f32_e32 vcc, s2, v2
	v_mul_f32_e32 v3, 0x4f800000, v2
	s_nop 0
	v_cndmask_b32_e32 v2, v2, v3, vcc
	v_sqrt_f32_e32 v3, v2
	s_nop 0
	v_add_u32_e32 v82, -1, v3
	v_fma_f32 v85, -v82, v3, v2
	v_cmp_ge_f32_e64 s[4:5], 0, v85
	v_add_u32_e32 v85, 1, v3
	s_nop 0
	v_cndmask_b32_e64 v82, v3, v82, s[4:5]
	v_fma_f32 v3, -v85, v3, v2
	v_cmp_lt_f32_e64 s[4:5], 0, v3
	s_nop 1
	v_cndmask_b32_e64 v3, v82, v85, s[4:5]
	v_mul_f32_e32 v82, 0x37800000, v3
	v_cndmask_b32_e32 v3, v3, v82, vcc
	v_cmp_class_f32_e32 vcc, v2, v216
	s_nop 1
	v_cndmask_b32_e32 v2, v3, v2, vcc
	v_div_scale_f32 v3, s[0:1], v2, v2, s3
	v_rcp_f32_e32 v82, v3
	s_nop 0
	v_fma_f32 v85, -v3, v82, 1.0
	v_fmac_f32_e32 v82, v85, v82
	v_div_scale_f32 v85, vcc, s3, v2, s3
	v_mul_f32_e32 v97, v85, v82
	v_fma_f32 v98, -v3, v97, v85
	v_fmac_f32_e32 v97, v98, v82
	v_fma_f32 v3, -v3, v97, v85
	v_div_fmas_f32 v3, v3, v82, v97
	v_div_fixup_f32 v82, v3, v2, s3
	v_or_b32_e32 v2, s20, v83
	v_mul_f32_e32 v83, v84, v82
	v_mov_b32_e32 v84, v206
	v_or_b32_e32 v2, s31, v2
	v_mov_b32_e32 v3, v1
	v_lshlrev_b64 v[2:3], 11, v[2:3]
	v_lshl_add_u64 v[2:3], s[90:91], 0, v[2:3]
	v_lshl_add_u64 v[2:3], v[2:3], 0, s[26:27]
	v_lshl_add_u64 v[2:3], v[2:3], 0, v[0:1]
	v_mul_f32_e32 v81, v81, v82
	v_mul_f32_e32 v80, v80, v82
	s_nop 0
	v_mul_f32_e32 v83, v84, v83
	v_cvt_pk_bf16_f32 v83, v83, v1
	v_mov_b32_e32 v84, v207
	s_nop 0
	global_store_short v[2:3], v83, off
	v_mul_f32_e32 v83, v96, v82
	s_nop 0
	v_mul_f32_e32 v83, v84, v83
	v_cvt_pk_bf16_f32 v83, v83, v1
	global_store_short v[2:3], v83, off offset:64
	v_mov_b32_e32 v83, v208
	s_nop 0
	v_mul_f32_e32 v81, v83, v81
	v_cvt_pk_bf16_f32 v81, v81, v1
	global_store_short v[2:3], v81, off offset:128
	v_mov_b32_e32 v81, v209
	v_or_b32_e32 v83, 10, v228
	s_nop 0
	v_mul_f32_e32 v80, v80, v81
	v_cvt_pk_bf16_f32 v80, v80, v1
	global_store_short v[2:3], v80, off offset:192
	v_lshl_add_u32 v80, v83, 9, v11
	ds_read2_b32 v[2:3], v80 offset1:32
	s_waitcnt lgkmcnt(0)
	v_fma_f32 v84, v118, v148, -v2
	v_fma_f32 v85, v134, v148, -v3
	ds_read2_b32 v[2:3], v80 offset0:64 offset1:96
	v_mul_f32_e32 v82, v85, v85
	v_fmac_f32_e32 v82, v84, v84
	s_waitcnt lgkmcnt(0)
	v_fma_f32 v81, v102, v148, -v2
	v_fmac_f32_e32 v82, v81, v81
	v_fma_f32 v80, v86, v148, -v3
	v_fmac_f32_e32 v82, v80, v80
	ds_bpermute_b32 v2, v10, v82
	s_waitcnt lgkmcnt(0)
	v_add_f32_e32 v2, v82, v2
	ds_bpermute_b32 v3, v9, v2
	s_waitcnt lgkmcnt(0)
; __device__ __forceinline__ unsigned cvtpk(float lo, float hi) { unsigned r; asm volatile("v_cvt_pk_bf16_f32 %0, %1, %2" : "=v"(r) : "v"(lo), "v"(hi)); return r; }
; __device__ __forceinline__ float sx(float v, int mask, int lane) { return __int_as_float(__builtin_amdgcn_ds_bpermute((lane ^ mask) << 2, __float_as_int(v))); }
; __device__ __forceinline__ int crow(int r, int hi) { return (r & 3) + 8 * (r >> 2) + 4 * hi; }
;     __device__ __forceinline__ long qtok(int wid, int i) const { return (long)b * T + res + dil * (qs0 + 32 * wid + i); }
;     __device__ __forceinline__ long qtok(int wid, int i) const { return (long)b * T + 256 * qb + 32 * wid + i; }
;     __device__ __forceinline__ long qtok(int wid, int i) const { return (long)b * T + 128 * qb + 32 * (wid & 3) + i; }
; template <class Pol>
; __device__ __forceinline__ void attn_unit(const Pol& P, LAS unsigned char* lds, const Ptrs& X, bf16x8& pq0, bf16x8& pq1, bf16x8& pq2, bf16x8& pq3, bf16x8& pk_, bf16x8& pv_, bool have, const Pol& Pn, bool hasn) {
;     ...
;         if (wid < 4) {
; #pragma unroll
;             for (int r = 0; r < 16; ++r) { const int row = 32 * wid + crow(r, hi); float s = 0.f;
; #pragma unroll
;                 for (int d = 0; d < NB; ++d) { const float y = o[d][r] * rli[r] - XB[row * 128 + d * 32 + r32]; o[d][r] = y; s += y * y; }
;                 s += sx(s, 1, lane); s += sx(s, 2, lane); s += sx(s, 4, lane); s += sx(s, 8, lane); s += sx(s, 16, lane);
;                 const float rs = (1.0f - LAM_INIT) / sqrtf(s * (1.0f / 128.f) + SUBLN_EPS);
;                 const long tok = P.qtok(wid, crow(r, hi));
; #pragma unroll
;                 for (int d = 0; d < NB; ++d) X.att[tok * D + P.h * 128 + d * 32 + r32] = (bf16_t)(cvtpk(o[d][r] * rs * X.subln[d * 32 + r32], 0.f) & 0xffffu); }
;         }
	v_add_f32_e32 v2, v2, v3
	ds_bpermute_b32 v3, v8, v2
	s_waitcnt lgkmcnt(0)
	v_add_f32_e32 v2, v2, v3
	ds_bpermute_b32 v3, v7, v2
	s_waitcnt lgkmcnt(0)
	v_add_f32_e32 v2, v2, v3
	ds_bpermute_b32 v3, v6, v2
	s_waitcnt lgkmcnt(0)
	v_add_f32_e32 v2, v2, v3
	v_fmamk_f32 v2, v2, 0x3c000000, v157
	v_cmp_gt_f32_e32 vcc, s2, v2
	v_mul_f32_e32 v3, 0x4f800000, v2
	s_nop 0
	v_cndmask_b32_e32 v2, v2, v3, vcc
	v_sqrt_f32_e32 v3, v2
	s_nop 0
	v_add_u32_e32 v82, -1, v3
	v_fma_f32 v86, -v82, v3, v2
	v_cmp_ge_f32_e64 s[4:5], 0, v86
	v_add_u32_e32 v86, 1, v3
	s_nop 0
	v_cndmask_b32_e64 v82, v3, v82, s[4:5]
	v_fma_f32 v3, -v86, v3, v2
	v_cmp_lt_f32_e64 s[4:5], 0, v3
	s_nop 1
	v_cndmask_b32_e64 v3, v82, v86, s[4:5]
	v_mul_f32_e32 v82, 0x37800000, v3
	v_cndmask_b32_e32 v3, v3, v82, vcc
	v_cmp_class_f32_e32 vcc, v2, v216
	s_nop 1
	v_cndmask_b32_e32 v2, v3, v2, vcc
	v_div_scale_f32 v3, s[0:1], v2, v2, s3
	v_rcp_f32_e32 v82, v3
	s_nop 0
	v_fma_f32 v86, -v3, v82, 1.0
	v_fmac_f32_e32 v82, v86, v82
	v_div_scale_f32 v86, vcc, s3, v2, s3
	v_mul_f32_e32 v96, v86, v82
	v_fma_f32 v97, -v3, v96, v86
	v_fmac_f32_e32 v96, v97, v82
	v_fma_f32 v3, -v3, v96, v86
	v_div_fmas_f32 v3, v3, v82, v96
	v_div_fixup_f32 v82, v3, v2, s3
	v_or_b32_e32 v2, s20, v83
	v_mul_f32_e32 v83, v84, v82
	v_mov_b32_e32 v84, v206
	v_or_b32_e32 v2, s31, v2
	v_mov_b32_e32 v3, v1
	v_lshlrev_b64 v[2:3], 11, v[2:3]
	v_lshl_add_u64 v[2:3], s[90:91], 0, v[2:3]
	v_lshl_add_u64 v[2:3], v[2:3], 0, s[26:27]
	v_lshl_add_u64 v[2:3], v[2:3], 0, v[0:1]
	v_mul_f32_e32 v81, v81, v82
	v_mul_f32_e32 v80, v80, v82
	s_nop 0
	v_mul_f32_e32 v83, v84, v83
	v_cvt_pk_bf16_f32 v83, v83, v1
	v_mov_b32_e32 v84, v207
	s_nop 0
	global_store_short v[2:3], v83, off
	v_mul_f32_e32 v83, v85, v82
	s_nop 0
	v_mul_f32_e32 v83, v84, v83
	v_cvt_pk_bf16_f32 v83, v83, v1
	global_store_short v[2:3], v83, off offset:64
	v_mov_b32_e32 v83, v208
	s_nop 0
	v_mul_f32_e32 v81, v83, v81
	v_cvt_pk_bf16_f32 v81, v81, v1
	global_store_short v[2:3], v81, off offset:128
	v_mov_b32_e32 v81, v209
	v_or_b32_e32 v83, 11, v228
	s_nop 0
	v_mul_f32_e32 v80, v80, v81
	v_cvt_pk_bf16_f32 v80, v80, v1
	global_store_short v[2:3], v80, off offset:192
	v_lshl_add_u32 v80, v83, 9, v11
	ds_read2_b32 v[2:3], v80 offset1:32
	s_waitcnt lgkmcnt(0)
	v_fma_f32 v84, v119, v147, -v2
	v_fma_f32 v85, v135, v147, -v3
	ds_read2_b32 v[2:3], v80 offset0:64 offset1:96
	v_mul_f32_e32 v82, v85, v85
	v_fmac_f32_e32 v82, v84, v84
	s_waitcnt lgkmcnt(0)
	v_fma_f32 v81, v103, v147, -v2
	v_fmac_f32_e32 v82, v81, v81
	v_fma_f32 v80, v87, v147, -v3
	v_fmac_f32_e32 v82, v80, v80
	ds_bpermute_b32 v2, v10, v82
	s_waitcnt lgkmcnt(0)
	v_add_f32_e32 v2, v82, v2
	ds_bpermute_b32 v3, v9, v2
	s_waitcnt lgkmcnt(0)
	v_add_f32_e32 v2, v2, v3
	ds_bpermute_b32 v3, v8, v2
	s_waitcnt lgkmcnt(0)
	v_add_f32_e32 v2, v2, v3
	ds_bpermute_b32 v3, v7, v2
	s_waitcnt lgkmcnt(0)
	v_add_f32_e32 v2, v2, v3
	ds_bpermute_b32 v3, v6, v2
	s_waitcnt lgkmcnt(0)
	v_add_f32_e32 v2, v2, v3
	v_fmamk_f32 v2, v2, 0x3c000000, v157
	v_cmp_gt_f32_e32 vcc, s2, v2
	v_mul_f32_e32 v3, 0x4f800000, v2
	s_nop 0
	v_cndmask_b32_e32 v2, v2, v3, vcc
	v_sqrt_f32_e32 v3, v2
	s_nop 0
	v_add_u32_e32 v82, -1, v3
	v_fma_f32 v86, -v82, v3, v2
	v_cmp_ge_f32_e64 s[4:5], 0, v86
	v_add_u32_e32 v86, 1, v3
	s_nop 0
	v_cndmask_b32_e64 v82, v3, v82, s[4:5]
	v_fma_f32 v3, -v86, v3, v2
	v_cmp_lt_f32_e64 s[4:5], 0, v3
	s_nop 1
	v_cndmask_b32_e64 v3, v82, v86, s[4:5]
	v_mul_f32_e32 v82, 0x37800000, v3
	v_cndmask_b32_e32 v3, v3, v82, vcc
	v_cmp_class_f32_e32 vcc, v2, v216
	s_nop 1
	v_cndmask_b32_e32 v2, v3, v2, vcc
	v_div_scale_f32 v3, s[0:1], v2, v2, s3
	v_rcp_f32_e32 v82, v3
	s_nop 0
	v_fma_f32 v86, -v3, v82, 1.0
	v_fmac_f32_e32 v82, v86, v82
	v_div_scale_f32 v86, vcc, s3, v2, s3
	v_mul_f32_e32 v87, v86, v82
	v_fma_f32 v96, -v3, v87, v86
	v_fmac_f32_e32 v87, v96, v82
	v_fma_f32 v3, -v3, v87, v86
	v_div_fmas_f32 v3, v3, v82, v87
	v_div_fixup_f32 v82, v3, v2, s3
	v_or_b32_e32 v2, s20, v83
	v_mul_f32_e32 v83, v84, v82
	v_mov_b32_e32 v84, v206
	v_or_b32_e32 v2, s31, v2
	v_mov_b32_e32 v3, v1
	v_lshlrev_b64 v[2:3], 11, v[2:3]
	v_lshl_add_u64 v[2:3], s[90:91], 0, v[2:3]
	v_lshl_add_u64 v[2:3], v[2:3], 0, s[26:27]
	v_lshl_add_u64 v[2:3], v[2:3], 0, v[0:1]
	v_mul_f32_e32 v81, v81, v82
	v_mul_f32_e32 v80, v80, v82
	s_nop 0
	v_mul_f32_e32 v83, v84, v83
	v_cvt_pk_bf16_f32 v83, v83, v1
	v_mov_b32_e32 v84, v207
	s_nop 0
	global_store_short v[2:3], v83, off
	v_mul_f32_e32 v83, v85, v82
	s_nop 0
	v_mul_f32_e32 v83, v84, v83
	v_cvt_pk_bf16_f32 v83, v83, v1
	global_store_short v[2:3], v83, off offset:64
	v_mov_b32_e32 v83, v208
	s_nop 0
	v_mul_f32_e32 v81, v83, v81
	v_cvt_pk_bf16_f32 v81, v81, v1
	global_store_short v[2:3], v81, off offset:128
	v_mov_b32_e32 v81, v209
	v_or_b32_e32 v83, 16, v228
	s_nop 0
	v_mul_f32_e32 v80, v80, v81
	v_cvt_pk_bf16_f32 v80, v80, v1
	global_store_short v[2:3], v80, off offset:192
	v_lshl_add_u32 v80, v83, 9, v11
	ds_read2_b32 v[2:3], v80 offset1:32
	s_waitcnt lgkmcnt(0)
	v_fma_f32 v84, v120, v146, -v2
	v_fma_f32 v85, v136, v146, -v3
	ds_read2_b32 v[2:3], v80 offset0:64 offset1:96
	v_mul_f32_e32 v82, v85, v85
	v_fmac_f32_e32 v82, v84, v84
	s_waitcnt lgkmcnt(0)
	v_fma_f32 v81, v104, v146, -v2
	v_fmac_f32_e32 v82, v81, v81
	v_fma_f32 v80, v88, v146, -v3
	v_fmac_f32_e32 v82, v80, v80
	ds_bpermute_b32 v2, v10, v82
	s_waitcnt lgkmcnt(0)
	v_add_f32_e32 v2, v82, v2
	ds_bpermute_b32 v3, v9, v2
	s_waitcnt lgkmcnt(0)
	v_add_f32_e32 v2, v2, v3
	ds_bpermute_b32 v3, v8, v2
	s_waitcnt lgkmcnt(0)
	v_add_f32_e32 v2, v2, v3
	ds_bpermute_b32 v3, v7, v2
	s_waitcnt lgkmcnt(0)
	v_add_f32_e32 v2, v2, v3
	ds_bpermute_b32 v3, v6, v2
	s_waitcnt lgkmcnt(0)
; __device__ __forceinline__ unsigned cvtpk(float lo, float hi) { unsigned r; asm volatile("v_cvt_pk_bf16_f32 %0, %1, %2" : "=v"(r) : "v"(lo), "v"(hi)); return r; }
; __device__ __forceinline__ float sx(float v, int mask, int lane) { return __int_as_float(__builtin_amdgcn_ds_bpermute((lane ^ mask) << 2, __float_as_int(v))); }
; __device__ __forceinline__ int crow(int r, int hi) { return (r & 3) + 8 * (r >> 2) + 4 * hi; }
;     __device__ __forceinline__ long qtok(int wid, int i) const { return (long)b * T + res + dil * (qs0 + 32 * wid + i); }
;     __device__ __forceinline__ long qtok(int wid, int i) const { return (long)b * T + 256 * qb + 32 * wid + i; }
;     __device__ __forceinline__ long qtok(int wid, int i) const { return (long)b * T + 128 * qb + 32 * (wid & 3) + i; }
; template <class Pol>
; __device__ __forceinline__ void attn_unit(const Pol& P, LAS unsigned char* lds, const Ptrs& X, bf16x8& pq0, bf16x8& pq1, bf16x8& pq2, bf16x8& pq3, bf16x8& pk_, bf16x8& pv_, bool have, const Pol& Pn, bool hasn) {
;     ...
;         if (wid < 4) {
; #pragma unroll
;             for (int r = 0; r < 16; ++r) { const int row = 32 * wid + crow(r, hi); float s = 0.f;
; #pragma unroll
;                 for (int d = 0; d < NB; ++d) { const float y = o[d][r] * rli[r] - XB[row * 128 + d * 32 + r32]; o[d][r] = y; s += y * y; }
;                 s += sx(s, 1, lane); s += sx(s, 2, lane); s += sx(s, 4, lane); s += sx(s, 8, lane); s += sx(s, 16, lane);
;                 const float rs = (1.0f - LAM_INIT) / sqrtf(s * (1.0f / 128.f) + SUBLN_EPS);
;                 const long tok = P.qtok(wid, crow(r, hi));
; #pragma unroll
;                 for (int d = 0; d < NB; ++d) X.att[tok * D + P.h * 128 + d * 32 + r32] = (bf16_t)(cvtpk(o[d][r] * rs * X.subln[d * 32 + r32], 0.f) & 0xffffu); }
;         }
	v_add_f32_e32 v2, v2, v3
	v_fmamk_f32 v2, v2, 0x3c000000, v157
	v_cmp_gt_f32_e32 vcc, s2, v2
	v_mul_f32_e32 v3, 0x4f800000, v2
	s_nop 0
	v_cndmask_b32_e32 v2, v2, v3, vcc
	v_sqrt_f32_e32 v3, v2
	s_nop 0
	v_add_u32_e32 v82, -1, v3
	v_fma_f32 v86, -v82, v3, v2
	v_cmp_ge_f32_e64 s[4:5], 0, v86
	v_add_u32_e32 v86, 1, v3
	s_nop 0
	v_cndmask_b32_e64 v82, v3, v82, s[4:5]
	v_fma_f32 v3, -v86, v3, v2
	v_cmp_lt_f32_e64 s[4:5], 0, v3
	s_nop 1
	v_cndmask_b32_e64 v3, v82, v86, s[4:5]
	v_mul_f32_e32 v82, 0x37800000, v3
	v_cndmask_b32_e32 v3, v3, v82, vcc
	v_cmp_class_f32_e32 vcc, v2, v216
	s_nop 1
	v_cndmask_b32_e32 v2, v3, v2, vcc
	v_div_scale_f32 v3, s[0:1], v2, v2, s3
	v_rcp_f32_e32 v82, v3
	s_nop 0
	v_fma_f32 v86, -v3, v82, 1.0
	v_fmac_f32_e32 v82, v86, v82
	v_div_scale_f32 v86, vcc, s3, v2, s3
	v_mul_f32_e32 v87, v86, v82
	v_fma_f32 v88, -v3, v87, v86
	v_fmac_f32_e32 v87, v88, v82
	v_fma_f32 v3, -v3, v87, v86
	v_div_fmas_f32 v3, v3, v82, v87
	v_div_fixup_f32 v82, v3, v2, s3
	v_or_b32_e32 v2, s20, v83
	v_mul_f32_e32 v83, v84, v82
	v_mov_b32_e32 v84, v206
	v_or_b32_e32 v2, s31, v2
	v_mov_b32_e32 v3, v1
	v_lshlrev_b64 v[2:3], 11, v[2:3]
	v_lshl_add_u64 v[2:3], s[90:91], 0, v[2:3]
	v_lshl_add_u64 v[2:3], v[2:3], 0, s[26:27]
	v_lshl_add_u64 v[2:3], v[2:3], 0, v[0:1]
	v_mul_f32_e32 v81, v81, v82
	v_mul_f32_e32 v80, v80, v82
	s_nop 0
	v_mul_f32_e32 v83, v84, v83
	v_cvt_pk_bf16_f32 v83, v83, v1
	v_mov_b32_e32 v84, v207
	s_nop 0
	global_store_short v[2:3], v83, off
	v_mul_f32_e32 v83, v85, v82
	s_nop 0
	v_mul_f32_e32 v83, v84, v83
	v_cvt_pk_bf16_f32 v83, v83, v1
	global_store_short v[2:3], v83, off offset:64
	v_mov_b32_e32 v83, v208
	s_nop 0
	v_mul_f32_e32 v81, v83, v81
	v_cvt_pk_bf16_f32 v81, v81, v1
	global_store_short v[2:3], v81, off offset:128
	v_mov_b32_e32 v81, v209
	v_or_b32_e32 v83, 17, v228
	s_nop 0
	v_mul_f32_e32 v80, v80, v81
	v_cvt_pk_bf16_f32 v80, v80, v1
	global_store_short v[2:3], v80, off offset:192
	v_lshl_add_u32 v80, v83, 9, v11
	ds_read2_b32 v[2:3], v80 offset1:32
	s_waitcnt lgkmcnt(0)
	v_fma_f32 v84, v121, v145, -v2
	v_fma_f32 v85, v137, v145, -v3
	ds_read2_b32 v[2:3], v80 offset0:64 offset1:96
	v_mul_f32_e32 v82, v85, v85
	v_fmac_f32_e32 v82, v84, v84
	s_waitcnt lgkmcnt(0)
	v_fma_f32 v81, v105, v145, -v2
	v_fmac_f32_e32 v82, v81, v81
	v_fma_f32 v80, v89, v145, -v3
	v_fmac_f32_e32 v82, v80, v80
	ds_bpermute_b32 v2, v10, v82
	s_waitcnt lgkmcnt(0)
	v_add_f32_e32 v2, v82, v2
	ds_bpermute_b32 v3, v9, v2
	s_waitcnt lgkmcnt(0)
	v_add_f32_e32 v2, v2, v3
	ds_bpermute_b32 v3, v8, v2
	s_waitcnt lgkmcnt(0)
	v_add_f32_e32 v2, v2, v3
	ds_bpermute_b32 v3, v7, v2
	s_waitcnt lgkmcnt(0)
	v_add_f32_e32 v2, v2, v3
	ds_bpermute_b32 v3, v6, v2
	s_waitcnt lgkmcnt(0)
	v_add_f32_e32 v2, v2, v3
	v_fmamk_f32 v2, v2, 0x3c000000, v157
	v_cmp_gt_f32_e32 vcc, s2, v2
	v_mul_f32_e32 v3, 0x4f800000, v2
	s_nop 0
	v_cndmask_b32_e32 v2, v2, v3, vcc
	v_sqrt_f32_e32 v3, v2
	s_nop 0
	v_add_u32_e32 v82, -1, v3
	v_fma_f32 v86, -v82, v3, v2
	v_cmp_ge_f32_e64 s[4:5], 0, v86
	v_add_u32_e32 v86, 1, v3
	s_nop 0
	v_cndmask_b32_e64 v82, v3, v82, s[4:5]
	v_fma_f32 v3, -v86, v3, v2
	v_cmp_lt_f32_e64 s[4:5], 0, v3
	s_nop 1
	v_cndmask_b32_e64 v3, v82, v86, s[4:5]
	v_mul_f32_e32 v82, 0x37800000, v3
	v_cndmask_b32_e32 v3, v3, v82, vcc
	v_cmp_class_f32_e32 vcc, v2, v216
	s_nop 1
	v_cndmask_b32_e32 v2, v3, v2, vcc
	v_div_scale_f32 v3, s[0:1], v2, v2, s3
	v_rcp_f32_e32 v82, v3
	s_nop 0
	v_fma_f32 v86, -v3, v82, 1.0
	v_fmac_f32_e32 v82, v86, v82
	v_div_scale_f32 v86, vcc, s3, v2, s3
	v_mul_f32_e32 v87, v86, v82
	v_fma_f32 v88, -v3, v87, v86
	v_fmac_f32_e32 v87, v88, v82
	v_fma_f32 v3, -v3, v87, v86
	v_div_fmas_f32 v3, v3, v82, v87
	v_div_fixup_f32 v82, v3, v2, s3
	v_or_b32_e32 v2, s20, v83
	v_mul_f32_e32 v83, v84, v82
	v_mov_b32_e32 v84, v206
	v_or_b32_e32 v2, s31, v2
	v_mov_b32_e32 v3, v1
	v_lshlrev_b64 v[2:3], 11, v[2:3]
	v_lshl_add_u64 v[2:3], s[90:91], 0, v[2:3]
	v_lshl_add_u64 v[2:3], v[2:3], 0, s[26:27]
	v_lshl_add_u64 v[2:3], v[2:3], 0, v[0:1]
	v_mul_f32_e32 v81, v81, v82
	v_mul_f32_e32 v80, v80, v82
	s_nop 0
	v_mul_f32_e32 v83, v84, v83
	v_cvt_pk_bf16_f32 v83, v83, v1
	v_mov_b32_e32 v84, v207
	s_nop 0
	global_store_short v[2:3], v83, off
	v_mul_f32_e32 v83, v85, v82
	s_nop 0
	v_mul_f32_e32 v83, v84, v83
	v_cvt_pk_bf16_f32 v83, v83, v1
	global_store_short v[2:3], v83, off offset:64
	v_mov_b32_e32 v83, v208
	s_nop 0
	v_mul_f32_e32 v81, v83, v81
	v_cvt_pk_bf16_f32 v81, v81, v1
	global_store_short v[2:3], v81, off offset:128
	v_mov_b32_e32 v81, v209
	v_or_b32_e32 v83, 18, v228
	s_nop 0
	v_mul_f32_e32 v80, v80, v81
	v_cvt_pk_bf16_f32 v80, v80, v1
	global_store_short v[2:3], v80, off offset:192
	v_lshl_add_u32 v80, v83, 9, v11
	ds_read2_b32 v[2:3], v80 offset1:32
	s_waitcnt lgkmcnt(0)
	v_fma_f32 v84, v122, v144, -v2
	v_fma_f32 v85, v138, v144, -v3
	ds_read2_b32 v[2:3], v80 offset0:64 offset1:96
	v_mul_f32_e32 v82, v85, v85
	v_fmac_f32_e32 v82, v84, v84
	s_waitcnt lgkmcnt(0)
	v_fma_f32 v81, v106, v144, -v2
	v_fmac_f32_e32 v82, v81, v81
	v_fma_f32 v80, v90, v144, -v3
	v_fmac_f32_e32 v82, v80, v80
	ds_bpermute_b32 v2, v10, v82
	s_waitcnt lgkmcnt(0)
	v_add_f32_e32 v2, v82, v2
	ds_bpermute_b32 v3, v9, v2
	s_waitcnt lgkmcnt(0)
	v_add_f32_e32 v2, v2, v3
	ds_bpermute_b32 v3, v8, v2
	s_waitcnt lgkmcnt(0)
	v_add_f32_e32 v2, v2, v3
	ds_bpermute_b32 v3, v7, v2
	s_waitcnt lgkmcnt(0)
	v_add_f32_e32 v2, v2, v3
	ds_bpermute_b32 v3, v6, v2
	s_waitcnt lgkmcnt(0)
; __device__ __forceinline__ unsigned cvtpk(float lo, float hi) { unsigned r; asm volatile("v_cvt_pk_bf16_f32 %0, %1, %2" : "=v"(r) : "v"(lo), "v"(hi)); return r; }
; __device__ __forceinline__ float sx(float v, int mask, int lane) { return __int_as_float(__builtin_amdgcn_ds_bpermute((lane ^ mask) << 2, __float_as_int(v))); }
; __device__ __forceinline__ int crow(int r, int hi) { return (r & 3) + 8 * (r >> 2) + 4 * hi; }
;     __device__ __forceinline__ long qtok(int wid, int i) const { return (long)b * T + res + dil * (qs0 + 32 * wid + i); }
;     __device__ __forceinline__ long qtok(int wid, int i) const { return (long)b * T + 256 * qb + 32 * wid + i; }
;     __device__ __forceinline__ long qtok(int wid, int i) const { return (long)b * T + 128 * qb + 32 * (wid & 3) + i; }
; template <class Pol>
; __device__ __forceinline__ void attn_unit(const Pol& P, LAS unsigned char* lds, const Ptrs& X, bf16x8& pq0, bf16x8& pq1, bf16x8& pq2, bf16x8& pq3, bf16x8& pk_, bf16x8& pv_, bool have, const Pol& Pn, bool hasn) {
;     ...
;         if (wid < 4) {
; #pragma unroll
;             for (int r = 0; r < 16; ++r) { const int row = 32 * wid + crow(r, hi); float s = 0.f;
; #pragma unroll
;                 for (int d = 0; d < NB; ++d) { const float y = o[d][r] * rli[r] - XB[row * 128 + d * 32 + r32]; o[d][r] = y; s += y * y; }
;                 s += sx(s, 1, lane); s += sx(s, 2, lane); s += sx(s, 4, lane); s += sx(s, 8, lane); s += sx(s, 16, lane);
;                 const float rs = (1.0f - LAM_INIT) / sqrtf(s * (1.0f / 128.f) + SUBLN_EPS);
;                 const long tok = P.qtok(wid, crow(r, hi));
; #pragma unroll
;                 for (int d = 0; d < NB; ++d) X.att[tok * D + P.h * 128 + d * 32 + r32] = (bf16_t)(cvtpk(o[d][r] * rs * X.subln[d * 32 + r32], 0.f) & 0xffffu); }
;         }
	v_add_f32_e32 v2, v2, v3
	v_fmamk_f32 v2, v2, 0x3c000000, v157
	v_cmp_gt_f32_e32 vcc, s2, v2
	v_mul_f32_e32 v3, 0x4f800000, v2
	s_nop 0
	v_cndmask_b32_e32 v2, v2, v3, vcc
	v_sqrt_f32_e32 v3, v2
	s_nop 0
	v_add_u32_e32 v82, -1, v3
	v_fma_f32 v86, -v82, v3, v2
	v_cmp_ge_f32_e64 s[4:5], 0, v86
	v_add_u32_e32 v86, 1, v3
	s_nop 0
	v_cndmask_b32_e64 v82, v3, v82, s[4:5]
	v_fma_f32 v3, -v86, v3, v2
	v_cmp_lt_f32_e64 s[4:5], 0, v3
	s_nop 1
	v_cndmask_b32_e64 v3, v82, v86, s[4:5]
	v_mul_f32_e32 v82, 0x37800000, v3
	v_cndmask_b32_e32 v3, v3, v82, vcc
	v_cmp_class_f32_e32 vcc, v2, v216
	s_nop 1
	v_cndmask_b32_e32 v2, v3, v2, vcc
	v_div_scale_f32 v3, s[0:1], v2, v2, s3
	v_rcp_f32_e32 v82, v3
	s_nop 0
	v_fma_f32 v86, -v3, v82, 1.0
	v_fmac_f32_e32 v82, v86, v82
	v_div_scale_f32 v86, vcc, s3, v2, s3
	v_mul_f32_e32 v87, v86, v82
	v_fma_f32 v88, -v3, v87, v86
	v_fmac_f32_e32 v87, v88, v82
	v_fma_f32 v3, -v3, v87, v86
	v_div_fmas_f32 v3, v3, v82, v87
	v_div_fixup_f32 v82, v3, v2, s3
	v_or_b32_e32 v2, s20, v83
	v_mul_f32_e32 v83, v84, v82
	v_mov_b32_e32 v84, v206
	v_or_b32_e32 v2, s31, v2
	v_mov_b32_e32 v3, v1
	v_lshlrev_b64 v[2:3], 11, v[2:3]
	v_lshl_add_u64 v[2:3], s[90:91], 0, v[2:3]
	v_lshl_add_u64 v[2:3], v[2:3], 0, s[26:27]
	v_lshl_add_u64 v[2:3], v[2:3], 0, v[0:1]
	v_mul_f32_e32 v81, v81, v82
	v_mul_f32_e32 v80, v80, v82
	s_nop 0
	v_mul_f32_e32 v83, v84, v83
	v_cvt_pk_bf16_f32 v83, v83, v1
	v_mov_b32_e32 v84, v207
	s_nop 0
	global_store_short v[2:3], v83, off
	v_mul_f32_e32 v83, v85, v82
	v_or_b32_e32 v82, 19, v228
	s_nop 0
	v_mul_f32_e32 v83, v84, v83
	v_cvt_pk_bf16_f32 v83, v83, v1
	global_store_short v[2:3], v83, off offset:64
	v_mov_b32_e32 v83, v208
	s_nop 0
	v_mul_f32_e32 v81, v83, v81
	v_cvt_pk_bf16_f32 v81, v81, v1
	global_store_short v[2:3], v81, off offset:128
	v_mov_b32_e32 v81, v209
	s_nop 0
	v_mul_f32_e32 v80, v80, v81
	v_cvt_pk_bf16_f32 v80, v80, v1
	global_store_short v[2:3], v80, off offset:192
	v_lshl_add_u32 v80, v82, 9, v11
	ds_read2_b32 v[2:3], v80 offset1:32
	s_waitcnt lgkmcnt(0)
	v_fma_f32 v83, v123, v15, -v2
	v_fma_f32 v84, v139, v15, -v3
	ds_read2_b32 v[2:3], v80 offset0:64 offset1:96
	v_mul_f32_e32 v81, v84, v84
	v_fmac_f32_e32 v81, v83, v83
	s_waitcnt lgkmcnt(0)
	v_fma_f32 v80, v107, v15, -v2
	v_fmac_f32_e32 v81, v80, v80
	v_fma_f32 v15, v91, v15, -v3
	v_fmac_f32_e32 v81, v15, v15
	ds_bpermute_b32 v2, v10, v81
	s_waitcnt lgkmcnt(0)
	v_add_f32_e32 v2, v81, v2
	ds_bpermute_b32 v3, v9, v2
	s_waitcnt lgkmcnt(0)
	v_add_f32_e32 v2, v2, v3
	ds_bpermute_b32 v3, v8, v2
	s_waitcnt lgkmcnt(0)
	v_add_f32_e32 v2, v2, v3
	ds_bpermute_b32 v3, v7, v2
	s_waitcnt lgkmcnt(0)
	v_add_f32_e32 v2, v2, v3
	ds_bpermute_b32 v3, v6, v2
	s_waitcnt lgkmcnt(0)
	v_add_f32_e32 v2, v2, v3
	v_fmamk_f32 v2, v2, 0x3c000000, v157
	v_cmp_gt_f32_e32 vcc, s2, v2
	v_mul_f32_e32 v3, 0x4f800000, v2
	s_nop 0
	v_cndmask_b32_e32 v2, v2, v3, vcc
	v_sqrt_f32_e32 v3, v2
	s_nop 0
	v_add_u32_e32 v81, -1, v3
	v_fma_f32 v85, -v81, v3, v2
	v_cmp_ge_f32_e64 s[4:5], 0, v85
	v_add_u32_e32 v85, 1, v3
	s_nop 0
	v_cndmask_b32_e64 v81, v3, v81, s[4:5]
	v_fma_f32 v3, -v85, v3, v2
	v_cmp_lt_f32_e64 s[4:5], 0, v3
	s_nop 1
	v_cndmask_b32_e64 v3, v81, v85, s[4:5]
	v_mul_f32_e32 v81, 0x37800000, v3
	v_cndmask_b32_e32 v3, v3, v81, vcc
	v_cmp_class_f32_e32 vcc, v2, v216
	s_nop 1
	v_cndmask_b32_e32 v2, v3, v2, vcc
	v_div_scale_f32 v3, s[0:1], v2, v2, s3
	v_rcp_f32_e32 v81, v3
	s_nop 0
	v_fma_f32 v85, -v3, v81, 1.0
	v_fmac_f32_e32 v81, v85, v81
	v_div_scale_f32 v85, vcc, s3, v2, s3
	v_mul_f32_e32 v86, v85, v81
	v_fma_f32 v87, -v3, v86, v85
	v_fmac_f32_e32 v86, v87, v81
	v_fma_f32 v3, -v3, v86, v85
	v_div_fmas_f32 v3, v3, v81, v86
	v_div_fixup_f32 v81, v3, v2, s3
	v_or_b32_e32 v2, s20, v82
	v_mul_f32_e32 v82, v83, v81
	v_mov_b32_e32 v83, v206
	v_or_b32_e32 v2, s31, v2
	v_mov_b32_e32 v3, v1
	v_lshlrev_b64 v[2:3], 11, v[2:3]
	v_lshl_add_u64 v[2:3], s[90:91], 0, v[2:3]
	v_lshl_add_u64 v[2:3], v[2:3], 0, s[26:27]
	v_lshl_add_u64 v[2:3], v[2:3], 0, v[0:1]
	v_mul_f32_e32 v80, v80, v81
	v_mul_f32_e32 v15, v15, v81
	s_nop 0
	v_mul_f32_e32 v82, v83, v82
	v_cvt_pk_bf16_f32 v82, v82, v1
	v_mov_b32_e32 v83, v207
	s_nop 0
	global_store_short v[2:3], v82, off
	v_mul_f32_e32 v82, v84, v81
	v_or_b32_e32 v81, 24, v228
	s_nop 0
	v_mul_f32_e32 v82, v83, v82
	v_cvt_pk_bf16_f32 v82, v82, v1
	global_store_short v[2:3], v82, off offset:64
	v_mov_b32_e32 v82, v208
	s_nop 0
	v_mul_f32_e32 v80, v82, v80
	v_cvt_pk_bf16_f32 v80, v80, v1
	global_store_short v[2:3], v80, off offset:128
	v_mov_b32_e32 v80, v209
	s_nop 0
	v_mul_f32_e32 v15, v15, v80
	v_cvt_pk_bf16_f32 v15, v15, v1
	global_store_short v[2:3], v15, off offset:192
	v_lshl_add_u32 v15, v81, 9, v11
	ds_read2_b32 v[2:3], v15 offset1:32
	s_waitcnt lgkmcnt(0)
	v_fma_f32 v82, v124, v14, -v2
	v_fma_f32 v83, v140, v14, -v3
	ds_read2_b32 v[2:3], v15 offset0:64 offset1:96
	v_mul_f32_e32 v80, v83, v83
	v_fmac_f32_e32 v80, v82, v82
	s_waitcnt lgkmcnt(0)
	v_fma_f32 v15, v108, v14, -v2
	v_fmac_f32_e32 v80, v15, v15
	v_fma_f32 v14, v92, v14, -v3
	v_fmac_f32_e32 v80, v14, v14
	ds_bpermute_b32 v2, v10, v80
	s_waitcnt lgkmcnt(0)
	v_add_f32_e32 v2, v80, v2
	ds_bpermute_b32 v3, v9, v2
	s_waitcnt lgkmcnt(0)
	v_add_f32_e32 v2, v2, v3
	ds_bpermute_b32 v3, v8, v2
	s_waitcnt lgkmcnt(0)
	v_add_f32_e32 v2, v2, v3
	ds_bpermute_b32 v3, v7, v2
	s_waitcnt lgkmcnt(0)
	v_add_f32_e32 v2, v2, v3
	ds_bpermute_b32 v3, v6, v2
	s_waitcnt lgkmcnt(0)
; __device__ __forceinline__ unsigned cvtpk(float lo, float hi) { unsigned r; asm volatile("v_cvt_pk_bf16_f32 %0, %1, %2" : "=v"(r) : "v"(lo), "v"(hi)); return r; }
; __device__ __forceinline__ float sx(float v, int mask, int lane) { return __int_as_float(__builtin_amdgcn_ds_bpermute((lane ^ mask) << 2, __float_as_int(v))); }
; __device__ __forceinline__ int crow(int r, int hi) { return (r & 3) + 8 * (r >> 2) + 4 * hi; }
;     __device__ __forceinline__ long qtok(int wid, int i) const { return (long)b * T + res + dil * (qs0 + 32 * wid + i); }
;     __device__ __forceinline__ long qtok(int wid, int i) const { return (long)b * T + 256 * qb + 32 * wid + i; }
;     __device__ __forceinline__ long qtok(int wid, int i) const { return (long)b * T + 128 * qb + 32 * (wid & 3) + i; }
; template <class Pol>
; __device__ __forceinline__ void attn_unit(const Pol& P, LAS unsigned char* lds, const Ptrs& X, bf16x8& pq0, bf16x8& pq1, bf16x8& pq2, bf16x8& pq3, bf16x8& pk_, bf16x8& pv_, bool have, const Pol& Pn, bool hasn) {
;     ...
;         if (wid < 4) {
; #pragma unroll
;             for (int r = 0; r < 16; ++r) { const int row = 32 * wid + crow(r, hi); float s = 0.f;
; #pragma unroll
;                 for (int d = 0; d < NB; ++d) { const float y = o[d][r] * rli[r] - XB[row * 128 + d * 32 + r32]; o[d][r] = y; s += y * y; }
;                 s += sx(s, 1, lane); s += sx(s, 2, lane); s += sx(s, 4, lane); s += sx(s, 8, lane); s += sx(s, 16, lane);
;                 const float rs = (1.0f - LAM_INIT) / sqrtf(s * (1.0f / 128.f) + SUBLN_EPS);
;                 const long tok = P.qtok(wid, crow(r, hi));
; #pragma unroll
;                 for (int d = 0; d < NB; ++d) X.att[tok * D + P.h * 128 + d * 32 + r32] = (bf16_t)(cvtpk(o[d][r] * rs * X.subln[d * 32 + r32], 0.f) & 0xffffu); }
;         }
	v_add_f32_e32 v2, v2, v3
	v_fmamk_f32 v2, v2, 0x3c000000, v157
	v_cmp_gt_f32_e32 vcc, s2, v2
	v_mul_f32_e32 v3, 0x4f800000, v2
	s_nop 0
	v_cndmask_b32_e32 v2, v2, v3, vcc
	v_sqrt_f32_e32 v3, v2
	s_nop 0
	v_add_u32_e32 v80, -1, v3
	v_fma_f32 v84, -v80, v3, v2
	v_cmp_ge_f32_e64 s[4:5], 0, v84
	v_add_u32_e32 v84, 1, v3
	s_nop 0
	v_cndmask_b32_e64 v80, v3, v80, s[4:5]
	v_fma_f32 v3, -v84, v3, v2
	v_cmp_lt_f32_e64 s[4:5], 0, v3
	s_nop 1
	v_cndmask_b32_e64 v3, v80, v84, s[4:5]
	v_mul_f32_e32 v80, 0x37800000, v3
	v_cndmask_b32_e32 v3, v3, v80, vcc
	v_cmp_class_f32_e32 vcc, v2, v216
	s_nop 1
	v_cndmask_b32_e32 v2, v3, v2, vcc
	v_div_scale_f32 v3, s[0:1], v2, v2, s3
	v_rcp_f32_e32 v80, v3
	s_nop 0
	v_fma_f32 v84, -v3, v80, 1.0
	v_fmac_f32_e32 v80, v84, v80
	v_div_scale_f32 v84, vcc, s3, v2, s3
	v_mul_f32_e32 v85, v84, v80
	v_fma_f32 v86, -v3, v85, v84
	v_fmac_f32_e32 v85, v86, v80
	v_fma_f32 v3, -v3, v85, v84
	v_div_fmas_f32 v3, v3, v80, v85
	v_div_fixup_f32 v80, v3, v2, s3
	v_or_b32_e32 v2, s20, v81
	v_mul_f32_e32 v81, v82, v80
	v_mov_b32_e32 v82, v206
	v_or_b32_e32 v2, s31, v2
	v_mov_b32_e32 v3, v1
	v_lshlrev_b64 v[2:3], 11, v[2:3]
	v_lshl_add_u64 v[2:3], s[90:91], 0, v[2:3]
	v_lshl_add_u64 v[2:3], v[2:3], 0, s[26:27]
	v_lshl_add_u64 v[2:3], v[2:3], 0, v[0:1]
	v_mul_f32_e32 v15, v15, v80
	v_mul_f32_e32 v14, v14, v80
	s_nop 0
	v_mul_f32_e32 v81, v82, v81
	v_cvt_pk_bf16_f32 v81, v81, v1
	v_mov_b32_e32 v82, v207
	s_nop 0
	global_store_short v[2:3], v81, off
	v_mul_f32_e32 v81, v83, v80
	v_or_b32_e32 v80, 25, v228
	s_nop 0
	v_mul_f32_e32 v81, v82, v81
	v_cvt_pk_bf16_f32 v81, v81, v1
	global_store_short v[2:3], v81, off offset:64
	v_mov_b32_e32 v81, v208
	s_nop 0
	v_mul_f32_e32 v15, v81, v15
	v_cvt_pk_bf16_f32 v15, v15, v1
	global_store_short v[2:3], v15, off offset:128
	v_mov_b32_e32 v15, v209
	s_nop 0
	v_mul_f32_e32 v14, v14, v15
	v_cvt_pk_bf16_f32 v14, v14, v1
	global_store_short v[2:3], v14, off offset:192
	v_lshl_add_u32 v14, v80, 9, v11
	ds_read2_b32 v[2:3], v14 offset1:32
	s_waitcnt lgkmcnt(0)
	v_fma_f32 v81, v125, v13, -v2
	v_fma_f32 v82, v141, v13, -v3
	ds_read2_b32 v[2:3], v14 offset0:64 offset1:96
	v_mul_f32_e32 v15, v82, v82
	v_fmac_f32_e32 v15, v81, v81
	s_waitcnt lgkmcnt(0)
	v_fma_f32 v14, v109, v13, -v2
	v_fmac_f32_e32 v15, v14, v14
	v_fma_f32 v13, v93, v13, -v3
	v_fmac_f32_e32 v15, v13, v13
	ds_bpermute_b32 v2, v10, v15
	s_waitcnt lgkmcnt(0)
	v_add_f32_e32 v2, v15, v2
	ds_bpermute_b32 v3, v9, v2
	s_waitcnt lgkmcnt(0)
	v_add_f32_e32 v2, v2, v3
	ds_bpermute_b32 v3, v8, v2
	s_waitcnt lgkmcnt(0)
	v_add_f32_e32 v2, v2, v3
	ds_bpermute_b32 v3, v7, v2
	s_waitcnt lgkmcnt(0)
	v_add_f32_e32 v2, v2, v3
	ds_bpermute_b32 v3, v6, v2
	s_waitcnt lgkmcnt(0)
	v_add_f32_e32 v2, v2, v3
	v_fmamk_f32 v2, v2, 0x3c000000, v157
	v_cmp_gt_f32_e32 vcc, s2, v2
	v_mul_f32_e32 v3, 0x4f800000, v2
	s_nop 0
	v_cndmask_b32_e32 v2, v2, v3, vcc
	v_sqrt_f32_e32 v3, v2
	s_nop 0
	v_add_u32_e32 v15, -1, v3
	v_fma_f32 v83, -v15, v3, v2
	v_cmp_ge_f32_e64 s[4:5], 0, v83
	v_add_u32_e32 v83, 1, v3
	s_nop 0
	v_cndmask_b32_e64 v15, v3, v15, s[4:5]
	v_fma_f32 v3, -v83, v3, v2
	v_cmp_lt_f32_e64 s[4:5], 0, v3
	s_nop 1
	v_cndmask_b32_e64 v3, v15, v83, s[4:5]
	v_mul_f32_e32 v15, 0x37800000, v3
	v_cndmask_b32_e32 v3, v3, v15, vcc
	v_cmp_class_f32_e32 vcc, v2, v216
	s_nop 1
	v_cndmask_b32_e32 v2, v3, v2, vcc
	v_div_scale_f32 v3, s[0:1], v2, v2, s3
	v_rcp_f32_e32 v15, v3
	s_nop 0
	v_fma_f32 v83, -v3, v15, 1.0
	v_fmac_f32_e32 v15, v83, v15
	v_div_scale_f32 v83, vcc, s3, v2, s3
	v_mul_f32_e32 v84, v83, v15
	v_fma_f32 v85, -v3, v84, v83
	v_fmac_f32_e32 v84, v85, v15
	v_fma_f32 v3, -v3, v84, v83
	v_div_fmas_f32 v3, v3, v15, v84
	v_div_fixup_f32 v15, v3, v2, s3
	v_or_b32_e32 v2, s20, v80
	v_mul_f32_e32 v80, v81, v15
	v_mov_b32_e32 v81, v206
	v_or_b32_e32 v2, s31, v2
	v_mov_b32_e32 v3, v1
	v_lshlrev_b64 v[2:3], 11, v[2:3]
	v_lshl_add_u64 v[2:3], s[90:91], 0, v[2:3]
	v_lshl_add_u64 v[2:3], v[2:3], 0, s[26:27]
	v_lshl_add_u64 v[2:3], v[2:3], 0, v[0:1]
	v_mul_f32_e32 v14, v14, v15
	v_mul_f32_e32 v13, v13, v15
	s_nop 0
	v_mul_f32_e32 v80, v81, v80
	v_cvt_pk_bf16_f32 v80, v80, v1
	v_mov_b32_e32 v81, v207
	s_nop 0
	global_store_short v[2:3], v80, off
	v_mul_f32_e32 v80, v82, v15
	v_or_b32_e32 v15, 26, v228
	s_nop 0
	v_mul_f32_e32 v80, v81, v80
	v_cvt_pk_bf16_f32 v80, v80, v1
	global_store_short v[2:3], v80, off offset:64
	v_mov_b32_e32 v80, v208
	s_nop 0
	v_mul_f32_e32 v14, v80, v14
	v_cvt_pk_bf16_f32 v14, v14, v1
	global_store_short v[2:3], v14, off offset:128
	v_mov_b32_e32 v14, v209
	s_nop 0
	v_mul_f32_e32 v13, v13, v14
	v_cvt_pk_bf16_f32 v13, v13, v1
	global_store_short v[2:3], v13, off offset:192
	v_lshl_add_u32 v13, v15, 9, v11
	ds_read2_b32 v[2:3], v13 offset1:32
	s_waitcnt lgkmcnt(0)
	v_fma_f32 v80, v126, v12, -v2
	v_fma_f32 v81, v142, v12, -v3
	ds_read2_b32 v[2:3], v13 offset0:64 offset1:96
	v_mul_f32_e32 v14, v81, v81
	v_fmac_f32_e32 v14, v80, v80
	s_waitcnt lgkmcnt(0)
; __device__ __forceinline__ unsigned cvtpk(float lo, float hi) { unsigned r; asm volatile("v_cvt_pk_bf16_f32 %0, %1, %2" : "=v"(r) : "v"(lo), "v"(hi)); return r; }
; __device__ __forceinline__ float sx(float v, int mask, int lane) { return __int_as_float(__builtin_amdgcn_ds_bpermute((lane ^ mask) << 2, __float_as_int(v))); }
; __device__ __forceinline__ int crow(int r, int hi) { return (r & 3) + 8 * (r >> 2) + 4 * hi; }
;     __device__ __forceinline__ long qtok(int wid, int i) const { return (long)b * T + res + dil * (qs0 + 32 * wid + i); }
;     __device__ __forceinline__ long qtok(int wid, int i) const { return (long)b * T + 256 * qb + 32 * wid + i; }
;     __device__ __forceinline__ long qtok(int wid, int i) const { return (long)b * T + 128 * qb + 32 * (wid & 3) + i; }
; template <class Pol>
; __device__ __forceinline__ void attn_unit(const Pol& P, LAS unsigned char* lds, const Ptrs& X, bf16x8& pq0, bf16x8& pq1, bf16x8& pq2, bf16x8& pq3, bf16x8& pk_, bf16x8& pv_, bool have, const Pol& Pn, bool hasn) {
;     ...
;         if (wid < 4) {
; #pragma unroll
;             for (int r = 0; r < 16; ++r) { const int row = 32 * wid + crow(r, hi); float s = 0.f;
; #pragma unroll
;                 for (int d = 0; d < NB; ++d) { const float y = o[d][r] * rli[r] - XB[row * 128 + d * 32 + r32]; o[d][r] = y; s += y * y; }
;                 s += sx(s, 1, lane); s += sx(s, 2, lane); s += sx(s, 4, lane); s += sx(s, 8, lane); s += sx(s, 16, lane);
;                 const float rs = (1.0f - LAM_INIT) / sqrtf(s * (1.0f / 128.f) + SUBLN_EPS);
;                 const long tok = P.qtok(wid, crow(r, hi));
; #pragma unroll
;                 for (int d = 0; d < NB; ++d) X.att[tok * D + P.h * 128 + d * 32 + r32] = (bf16_t)(cvtpk(o[d][r] * rs * X.subln[d * 32 + r32], 0.f) & 0xffffu); }
;         }
	v_fma_f32 v13, v110, v12, -v2
	v_fmac_f32_e32 v14, v13, v13
	v_fma_f32 v12, v94, v12, -v3
	v_fmac_f32_e32 v14, v12, v12
	ds_bpermute_b32 v2, v10, v14
	s_waitcnt lgkmcnt(0)
	v_add_f32_e32 v2, v14, v2
	ds_bpermute_b32 v3, v9, v2
	s_waitcnt lgkmcnt(0)
	v_add_f32_e32 v2, v2, v3
	ds_bpermute_b32 v3, v8, v2
	s_waitcnt lgkmcnt(0)
	v_add_f32_e32 v2, v2, v3
	ds_bpermute_b32 v3, v7, v2
	s_waitcnt lgkmcnt(0)
	v_add_f32_e32 v2, v2, v3
	ds_bpermute_b32 v3, v6, v2
	s_waitcnt lgkmcnt(0)
	v_add_f32_e32 v2, v2, v3
	v_fmamk_f32 v2, v2, 0x3c000000, v157
	v_cmp_gt_f32_e32 vcc, s2, v2
	v_mul_f32_e32 v3, 0x4f800000, v2
	s_nop 0
	v_cndmask_b32_e32 v2, v2, v3, vcc
	v_sqrt_f32_e32 v3, v2
	s_nop 0
	v_add_u32_e32 v14, -1, v3
	v_fma_f32 v82, -v14, v3, v2
	v_cmp_ge_f32_e64 s[4:5], 0, v82
	v_add_u32_e32 v82, 1, v3
	s_nop 0
	v_cndmask_b32_e64 v14, v3, v14, s[4:5]
	v_fma_f32 v3, -v82, v3, v2
	v_cmp_lt_f32_e64 s[4:5], 0, v3
	s_nop 1
	v_cndmask_b32_e64 v3, v14, v82, s[4:5]
	v_mul_f32_e32 v14, 0x37800000, v3
	v_cndmask_b32_e32 v3, v3, v14, vcc
	v_cmp_class_f32_e32 vcc, v2, v216
	s_nop 1
	v_cndmask_b32_e32 v2, v3, v2, vcc
	v_div_scale_f32 v3, s[0:1], v2, v2, s3
	v_rcp_f32_e32 v14, v3
	s_nop 0
	v_fma_f32 v82, -v3, v14, 1.0
	v_fmac_f32_e32 v14, v82, v14
	v_div_scale_f32 v82, vcc, s3, v2, s3
	v_mul_f32_e32 v83, v82, v14
	v_fma_f32 v84, -v3, v83, v82
	v_fmac_f32_e32 v83, v84, v14
	v_fma_f32 v3, -v3, v83, v82
	v_div_fmas_f32 v3, v3, v14, v83
	v_div_fixup_f32 v14, v3, v2, s3
	v_or_b32_e32 v2, s20, v15
	v_mul_f32_e32 v15, v80, v14
	v_mov_b32_e32 v80, v206
	v_or_b32_e32 v2, s31, v2
	v_mov_b32_e32 v3, v1
	v_lshlrev_b64 v[2:3], 11, v[2:3]
	v_lshl_add_u64 v[2:3], s[90:91], 0, v[2:3]
	v_lshl_add_u64 v[2:3], v[2:3], 0, s[26:27]
	v_lshl_add_u64 v[2:3], v[2:3], 0, v[0:1]
	v_mul_f32_e32 v13, v13, v14
	v_mul_f32_e32 v12, v12, v14
	s_nop 0
	v_mul_f32_e32 v15, v80, v15
	v_cvt_pk_bf16_f32 v15, v15, v1
	v_mov_b32_e32 v80, v207
	s_nop 0
	global_store_short v[2:3], v15, off
	v_mul_f32_e32 v15, v81, v14
	s_nop 0
	v_mul_f32_e32 v15, v80, v15
	v_cvt_pk_bf16_f32 v15, v15, v1
	global_store_short v[2:3], v15, off offset:64
	v_mov_b32_e32 v15, v208
	s_nop 0
	v_mul_f32_e32 v13, v15, v13
	v_cvt_pk_bf16_f32 v13, v13, v1
	global_store_short v[2:3], v13, off offset:128
	v_mov_b32_e32 v13, v209
	s_nop 0
	v_mul_f32_e32 v12, v12, v13
	v_or_b32_e32 v13, 27, v228
	v_lshl_add_u32 v11, v13, 9, v11
	v_cvt_pk_bf16_f32 v12, v12, v1
	global_store_short v[2:3], v12, off offset:192
	ds_read2_b32 v[2:3], v11 offset1:32
	s_waitcnt lgkmcnt(0)
	v_fma_f32 v14, v127, v5, -v2
	v_fma_f32 v12, v143, v5, -v3
	ds_read2_b32 v[2:3], v11 offset0:64 offset1:96
	v_mul_f32_e32 v15, v12, v12
	v_fmac_f32_e32 v15, v14, v14
	s_waitcnt lgkmcnt(0)
	v_fma_f32 v11, v111, v5, -v2
	v_fmac_f32_e32 v15, v11, v11
	v_fma_f32 v5, v95, v5, -v3
	v_fmac_f32_e32 v15, v5, v5
	ds_bpermute_b32 v2, v10, v15
	s_waitcnt lgkmcnt(0)
	v_add_f32_e32 v2, v15, v2
	ds_bpermute_b32 v3, v9, v2
	s_waitcnt lgkmcnt(0)
	v_add_f32_e32 v2, v2, v3
	ds_bpermute_b32 v3, v8, v2
	s_waitcnt lgkmcnt(0)
	v_add_f32_e32 v2, v2, v3
	ds_bpermute_b32 v3, v7, v2
	s_waitcnt lgkmcnt(0)
	v_add_f32_e32 v2, v2, v3
	ds_bpermute_b32 v3, v6, v2
	s_waitcnt lgkmcnt(0)
	v_add_f32_e32 v2, v2, v3
	v_fmamk_f32 v2, v2, 0x3c000000, v157
	v_cmp_gt_f32_e32 vcc, s2, v2
	v_mul_f32_e32 v3, 0x4f800000, v2
	s_nop 0
	v_cndmask_b32_e32 v2, v2, v3, vcc
	v_sqrt_f32_e32 v3, v2
	s_nop 0
	v_add_u32_e32 v6, -1, v3
	v_fma_f32 v7, -v6, v3, v2
	v_cmp_ge_f32_e64 s[4:5], 0, v7
	v_add_u32_e32 v7, 1, v3
	s_nop 0
	v_cndmask_b32_e64 v6, v3, v6, s[4:5]
	v_fma_f32 v3, -v7, v3, v2
	v_cmp_lt_f32_e64 s[4:5], 0, v3
	s_nop 1
	v_cndmask_b32_e64 v3, v6, v7, s[4:5]
	v_mul_f32_e32 v6, 0x37800000, v3
	v_cndmask_b32_e32 v3, v3, v6, vcc
	v_cmp_class_f32_e32 vcc, v2, v216
	s_nop 1
	v_cndmask_b32_e32 v2, v3, v2, vcc
	v_div_scale_f32 v3, s[0:1], v2, v2, s3
	v_rcp_f32_e32 v6, v3
	s_nop 0
	v_fma_f32 v7, -v3, v6, 1.0
	v_fmac_f32_e32 v6, v7, v6
	v_div_scale_f32 v7, vcc, s3, v2, s3
	v_mul_f32_e32 v8, v7, v6
	v_fma_f32 v9, -v3, v8, v7
	v_fmac_f32_e32 v8, v9, v6
	v_fma_f32 v3, -v3, v8, v7
	v_div_fmas_f32 v3, v3, v6, v8
	v_mov_b32_e32 v8, v206
	v_div_fixup_f32 v6, v3, v2, s3
	v_or_b32_e32 v2, s20, v13
	v_or_b32_e32 v2, s31, v2
	v_mov_b32_e32 v3, v1
	v_lshlrev_b64 v[2:3], 11, v[2:3]
	v_mul_f32_e32 v7, v14, v6
	v_lshl_add_u64 v[2:3], s[90:91], 0, v[2:3]
	v_lshl_add_u64 v[2:3], v[2:3], 0, s[26:27]
	v_lshl_add_u64 v[2:3], v[2:3], 0, v[0:1]
	v_mul_f32_e32 v0, v12, v6
	s_nop 0
	v_mul_f32_e32 v7, v8, v7
	v_cvt_pk_bf16_f32 v7, v7, v1
	global_store_short v[2:3], v7, off
	v_mov_b32_e32 v7, v207
	s_nop 0
	v_mul_f32_e32 v0, v7, v0
	v_cvt_pk_bf16_f32 v0, v0, v1
	v_mov_b32_e32 v7, v208
	s_nop 0
	global_store_short v[2:3], v0, off offset:64
	v_mul_f32_e32 v0, v11, v6
	s_nop 0
	v_mul_f32_e32 v0, v7, v0
	v_cvt_pk_bf16_f32 v0, v0, v1
	v_mov_b32_e32 v4, v209
	s_nop 0
	global_store_short v[2:3], v0, off offset:128
	v_mul_f32_e32 v0, v5, v6
	s_nop 0
	v_mul_f32_e32 v0, v0, v4
	v_cvt_pk_bf16_f32 v0, v0, v1
	global_store_short v[2:3], v0, off offset:192

; __device__ __forceinline__ unsigned cvtpk(float lo, float hi) { unsigned r; asm volatile("v_cvt_pk_bf16_f32 %0, %1, %2" : "=v"(r) : "v"(lo), "v"(hi)); return r; }
; __device__ __forceinline__ float sx(float v, int mask, int lane) { return __int_as_float(__builtin_amdgcn_ds_bpermute((lane ^ mask) << 2, __float_as_int(v))); }
; __device__ __forceinline__ int crow(int r, int hi) { return (r & 3) + 8 * (r >> 2) + 4 * hi; }
;     __device__ __forceinline__ long qtok(int wid, int i) const { return (long)b * T + res + dil * (qs0 + 32 * wid + i); }
;     __device__ __forceinline__ long qtok(int wid, int i) const { return (long)b * T + 256 * qb + 32 * wid + i; }
;     __device__ __forceinline__ long qtok(int wid, int i) const { return (long)b * T + 128 * qb + 32 * (wid & 3) + i; }
; template <class Pol>
; __device__ __forceinline__ void attn_unit(const Pol& P, LAS unsigned char* lds, const Ptrs& X, bf16x8& pq0, bf16x8& pq1, bf16x8& pq2, bf16x8& pq3, bf16x8& pk_, bf16x8& pv_, bool have, const Pol& Pn, bool hasn) {
;     ...
;         if (wid < 4) {
; #pragma unroll
;             for (int r = 0; r < 16; ++r) { const int row = 32 * wid + crow(r, hi); float s = 0.f;
; #pragma unroll
;                 for (int d = 0; d < NB; ++d) { const float y = o[d][r] * rli[r] - XB[row * 128 + d * 32 + r32]; o[d][r] = y; s += y * y; }
;                 s += sx(s, 1, lane); s += sx(s, 2, lane); s += sx(s, 4, lane); s += sx(s, 8, lane); s += sx(s, 16, lane);
;                 const float rs = (1.0f - LAM_INIT) / sqrtf(s * (1.0f / 128.f) + SUBLN_EPS);
;                 const long tok = P.qtok(wid, crow(r, hi));
; #pragma unroll
;                 for (int d = 0; d < NB; ++d) X.att[tok * D + P.h * 128 + d * 32 + r32] = (bf16_t)(cvtpk(o[d][r] * rs * X.subln[d * 32 + r32], 0.f) & 0xffffu); }
;         }
.LBB0_359:
	s_cmp_gt_i32 s2, 3
	s_waitcnt lgkmcnt(0)
	s_barrier
	s_cbranch_scc1 .LBB0_361
	s_lshl_b32 s0, s2, 14
	s_add_i32 s0, s0, 0
	s_add_i32 s0, s0, 0x11000
	v_lshlrev_b32_e32 v6, 2, v204
	v_add_u32_e32 v13, s0, v6
	v_lshlrev_b32_e32 v2, 2, v229
	v_lshl_add_u32 v4, v228, 11, v13
	v_xor_b32_e32 v12, 4, v2
	v_xor_b32_e32 v11, 8, v2
	v_xor_b32_e32 v10, 16, v2
	v_xor_b32_e32 v9, 32, v2
	v_xor_b32_e32 v8, 64, v2
	ds_read2_b32 v[2:3], v4 offset1:32
	v_mov_b32_e32 v157, 0x3727c5ac
	s_mov_b32 s2, 0xf800000
	s_mov_b32 s3, 0x3f24fd5c
	v_readlane_b32 s6, v254, 27
	s_waitcnt lgkmcnt(0)
	v_fma_f32 v156, v112, v0, -v2
	v_fma_f32 v128, v128, v0, -v3
	ds_read2_b32 v[2:3], v4 offset0:64 offset1:96
	v_mul_f32_e32 v5, v128, v128
	v_fmac_f32_e32 v5, v156, v156
	v_readlane_b32 s7, v254, 28
	s_nop 4
	global_load_dword v192, v6, s[6:7]
	global_load_dword v193, v6, s[6:7] offset:128
	global_load_dword v194, v6, s[6:7] offset:256
	global_load_dword v195, v6, s[6:7] offset:384
	s_lshl_b32 s26, s30, 1
	s_waitcnt lgkmcnt(0)
	v_fma_f32 v96, v96, v0, -v2
	v_fmac_f32_e32 v5, v96, v96
	v_fma_f32 v80, v80, v0, -v3
	v_fmac_f32_e32 v5, v80, v80
	ds_bpermute_b32 v0, v12, v5
	s_waitcnt lgkmcnt(0)
	v_add_f32_e32 v0, v5, v0
	ds_bpermute_b32 v2, v11, v0
	s_waitcnt lgkmcnt(0)
	v_add_f32_e32 v0, v0, v2
	ds_bpermute_b32 v2, v10, v0
	s_waitcnt lgkmcnt(0)
	v_add_f32_e32 v0, v0, v2
	ds_bpermute_b32 v2, v9, v0
	s_waitcnt lgkmcnt(0)
	v_add_f32_e32 v0, v0, v2
	ds_bpermute_b32 v2, v8, v0
	s_waitcnt lgkmcnt(0)
	v_add_f32_e32 v0, v0, v2
	v_fmamk_f32 v0, v0, 0x3c000000, v157
	v_cmp_gt_f32_e32 vcc, s2, v0
	v_mul_f32_e32 v2, 0x4f800000, v0
	s_nop 0
	v_cndmask_b32_e32 v0, v0, v2, vcc
	v_sqrt_f32_e32 v2, v0
	s_nop 0
	v_add_u32_e32 v3, -1, v2
	v_fma_f32 v4, -v3, v2, v0
	v_cmp_ge_f32_e64 s[4:5], 0, v4
	v_add_u32_e32 v4, 1, v2
	s_nop 0
	v_cndmask_b32_e64 v3, v2, v3, s[4:5]
	v_fma_f32 v2, -v4, v2, v0
	v_cmp_lt_f32_e64 s[4:5], 0, v2
	s_nop 1
	v_cndmask_b32_e64 v2, v3, v4, s[4:5]
	v_mul_f32_e32 v3, 0x37800000, v2
	v_cndmask_b32_e32 v2, v2, v3, vcc
	v_cmp_class_f32_e32 vcc, v0, v216
	s_nop 1
	v_cndmask_b32_e32 v0, v2, v0, vcc
	v_div_scale_f32 v2, s[0:1], v0, v0, s3
	v_rcp_f32_e32 v3, v2
	s_nop 0
	v_fma_f32 v4, -v2, v3, 1.0
	v_fmac_f32_e32 v3, v4, v3
	v_div_scale_f32 v4, vcc, s3, v0, s3
	v_mul_f32_e32 v5, v4, v3
	v_fma_f32 v112, -v2, v5, v4
	v_fmac_f32_e32 v5, v112, v3
	v_fma_f32 v2, -v2, v5, v4
	v_div_fmas_f32 v2, v2, v3, v5
	v_div_fixup_f32 v112, v2, v0, s3
	v_or_b32_e32 v0, s21, v227
	v_mov_b32_e32 v3, s9
	v_or_b32_e32 v2, s8, v0
	v_lshlrev_b64 v[4:5], 11, v[2:3]
	s_waitcnt vmcnt(0)
	v_mov_b32_e32 v2, v192
	v_mul_f32_e32 v0, v156, v112
	v_lshl_add_u64 v[4:5], s[90:91], 0, v[4:5]
	v_lshl_add_u64 v[4:5], v[4:5], 0, s[26:27]
	s_nop 0
	v_mul_f32_e32 v0, v2, v0
	v_cvt_pk_bf16_f32 v2, v0, v1
	v_lshlrev_b32_e32 v0, 1, v204
	v_lshl_add_u64 v[4:5], v[4:5], 0, v[0:1]
	global_store_short v[4:5], v2, off
	v_mul_f32_e32 v2, v128, v112
	v_mov_b32_e32 v128, v193
	s_nop 0
	v_mul_f32_e32 v2, v128, v2
	v_cvt_pk_bf16_f32 v2, v2, v1
	global_store_short v[4:5], v2, off offset:64
	v_mul_f32_e32 v2, v96, v112
	v_mov_b32_e32 v96, v194
	s_nop 0
	v_mul_f32_e32 v2, v96, v2
	v_cvt_pk_bf16_f32 v2, v2, v1
	global_store_short v[4:5], v2, off offset:128
	v_mul_f32_e32 v2, v80, v112
	v_mov_b32_e32 v80, v195
	s_nop 0
	v_mul_f32_e32 v2, v2, v80
	v_cvt_pk_bf16_f32 v2, v2, v1
	global_store_short v[4:5], v2, off offset:192
	v_or_b32_e32 v2, 1, v227
	v_lshl_add_u32 v80, v2, 9, v13
	ds_read2_b32 v[4:5], v80 offset1:32
	v_or_b32_e32 v2, s21, v2
	v_or_b32_e32 v2, s8, v2
	s_waitcnt lgkmcnt(0)
	v_fma_f32 v112, v113, v155, -v4
	v_fma_f32 v113, v129, v155, -v5
	ds_read2_b32 v[4:5], v80 offset0:64 offset1:96
	v_mul_f32_e32 v128, v113, v113
	v_fmac_f32_e32 v128, v112, v112
	s_waitcnt lgkmcnt(0)
	v_fma_f32 v96, v97, v155, -v4
	v_fmac_f32_e32 v128, v96, v96
	v_fma_f32 v80, v81, v155, -v5
	v_fmac_f32_e32 v128, v80, v80
	ds_bpermute_b32 v4, v12, v128
	s_waitcnt lgkmcnt(0)
	v_add_f32_e32 v4, v128, v4
	ds_bpermute_b32 v5, v11, v4
	s_waitcnt lgkmcnt(0)
	v_add_f32_e32 v4, v4, v5
	ds_bpermute_b32 v5, v10, v4
	s_waitcnt lgkmcnt(0)
	v_add_f32_e32 v4, v4, v5
	ds_bpermute_b32 v5, v9, v4
	s_waitcnt lgkmcnt(0)
	v_add_f32_e32 v4, v4, v5
	ds_bpermute_b32 v5, v8, v4
	s_waitcnt lgkmcnt(0)
	v_add_f32_e32 v4, v4, v5
	v_fmamk_f32 v4, v4, 0x3c000000, v157
	v_cmp_gt_f32_e32 vcc, s2, v4
	v_mul_f32_e32 v5, 0x4f800000, v4
	s_nop 0
	v_cndmask_b32_e32 v4, v4, v5, vcc
	v_sqrt_f32_e32 v5, v4
	s_nop 0
	v_add_u32_e32 v81, -1, v5
	v_fma_f32 v97, -v81, v5, v4
	v_cmp_ge_f32_e64 s[4:5], 0, v97
	v_add_u32_e32 v97, 1, v5
	s_nop 0
	v_cndmask_b32_e64 v81, v5, v81, s[4:5]
	v_fma_f32 v5, -v97, v5, v4
	v_cmp_lt_f32_e64 s[4:5], 0, v5
	s_nop 1
	v_cndmask_b32_e64 v5, v81, v97, s[4:5]
	v_mul_f32_e32 v81, 0x37800000, v5
	v_cndmask_b32_e32 v5, v5, v81, vcc
	v_cmp_class_f32_e32 vcc, v4, v216
	s_nop 1
	v_cndmask_b32_e32 v4, v5, v4, vcc
	v_div_scale_f32 v5, s[0:1], v4, v4, s3
	v_rcp_f32_e32 v81, v5
	s_nop 0
	v_fma_f32 v97, -v5, v81, 1.0
	v_fmac_f32_e32 v81, v97, v81
	v_div_scale_f32 v97, vcc, s3, v4, s3
	v_mul_f32_e32 v128, v97, v81
	v_fma_f32 v129, -v5, v128, v97
	v_fmac_f32_e32 v128, v129, v81
	v_fma_f32 v5, -v5, v128, v97
	v_mov_b32_e32 v97, v192
	v_div_fmas_f32 v5, v5, v81, v128
	v_div_fixup_f32 v81, v5, v4, s3
	v_lshlrev_b64 v[4:5], 11, v[2:3]
	v_mul_f32_e32 v2, v112, v81
	v_lshl_add_u64 v[4:5], s[90:91], 0, v[4:5]
	v_lshl_add_u64 v[4:5], v[4:5], 0, s[26:27]
	v_lshl_add_u64 v[4:5], v[4:5], 0, v[0:1]
	s_nop 0
	v_mul_f32_e32 v2, v97, v2
	v_cvt_pk_bf16_f32 v2, v2, v1
	v_mov_b32_e32 v97, v193
	s_nop 0
	global_store_short v[4:5], v2, off
	v_mul_f32_e32 v2, v113, v81
	s_nop 0
	v_mul_f32_e32 v2, v97, v2
	v_cvt_pk_bf16_f32 v2, v2, v1
	global_store_short v[4:5], v2, off offset:64
	v_mul_f32_e32 v2, v96, v81
	v_mov_b32_e32 v96, v194
	s_nop 0
	v_mul_f32_e32 v2, v96, v2
	v_cvt_pk_bf16_f32 v2, v2, v1
	global_store_short v[4:5], v2, off offset:128
	v_mul_f32_e32 v2, v80, v81
	v_mov_b32_e32 v80, v195
	s_nop 0
	v_mul_f32_e32 v2, v2, v80
	v_cvt_pk_bf16_f32 v2, v2, v1
	global_store_short v[4:5], v2, off offset:192
	v_or_b32_e32 v2, 2, v227
	v_lshl_add_u32 v80, v2, 9, v13
	ds_read2_b32 v[4:5], v80 offset1:32
	v_or_b32_e32 v2, s21, v2
	v_or_b32_e32 v2, s8, v2
	s_waitcnt lgkmcnt(0)
; __device__ __forceinline__ unsigned cvtpk(float lo, float hi) { unsigned r; asm volatile("v_cvt_pk_bf16_f32 %0, %1, %2" : "=v"(r) : "v"(lo), "v"(hi)); return r; }
; __device__ __forceinline__ float sx(float v, int mask, int lane) { return __int_as_float(__builtin_amdgcn_ds_bpermute((lane ^ mask) << 2, __float_as_int(v))); }
; __device__ __forceinline__ int crow(int r, int hi) { return (r & 3) + 8 * (r >> 2) + 4 * hi; }
;     __device__ __forceinline__ long qtok(int wid, int i) const { return (long)b * T + res + dil * (qs0 + 32 * wid + i); }
;     __device__ __forceinline__ long qtok(int wid, int i) const { return (long)b * T + 256 * qb + 32 * wid + i; }
;     __device__ __forceinline__ long qtok(int wid, int i) const { return (long)b * T + 128 * qb + 32 * (wid & 3) + i; }
; template <class Pol>
; __device__ __forceinline__ void attn_unit(const Pol& P, LAS unsigned char* lds, const Ptrs& X, bf16x8& pq0, bf16x8& pq1, bf16x8& pq2, bf16x8& pq3, bf16x8& pk_, bf16x8& pv_, bool have, const Pol& Pn, bool hasn) {
;     ...
;         if (wid < 4) {
; #pragma unroll
;             for (int r = 0; r < 16; ++r) { const int row = 32 * wid + crow(r, hi); float s = 0.f;
; #pragma unroll
;                 for (int d = 0; d < NB; ++d) { const float y = o[d][r] * rli[r] - XB[row * 128 + d * 32 + r32]; o[d][r] = y; s += y * y; }
;                 s += sx(s, 1, lane); s += sx(s, 2, lane); s += sx(s, 4, lane); s += sx(s, 8, lane); s += sx(s, 16, lane);
;                 const float rs = (1.0f - LAM_INIT) / sqrtf(s * (1.0f / 128.f) + SUBLN_EPS);
;                 const long tok = P.qtok(wid, crow(r, hi));
; #pragma unroll
;                 for (int d = 0; d < NB; ++d) X.att[tok * D + P.h * 128 + d * 32 + r32] = (bf16_t)(cvtpk(o[d][r] * rs * X.subln[d * 32 + r32], 0.f) & 0xffffu); }
;         }
	v_fma_f32 v96, v114, v154, -v4
	v_fma_f32 v97, v130, v154, -v5
	ds_read2_b32 v[4:5], v80 offset0:64 offset1:96
	v_mul_f32_e32 v112, v97, v97
	v_fmac_f32_e32 v112, v96, v96
	s_waitcnt lgkmcnt(0)
	v_fma_f32 v81, v98, v154, -v4
	v_fmac_f32_e32 v112, v81, v81
	v_fma_f32 v80, v82, v154, -v5
	v_fmac_f32_e32 v112, v80, v80
	ds_bpermute_b32 v4, v12, v112
	s_waitcnt lgkmcnt(0)
	v_add_f32_e32 v4, v112, v4
	ds_bpermute_b32 v5, v11, v4
	s_waitcnt lgkmcnt(0)
	v_add_f32_e32 v4, v4, v5
	ds_bpermute_b32 v5, v10, v4
	s_waitcnt lgkmcnt(0)
	v_add_f32_e32 v4, v4, v5
	ds_bpermute_b32 v5, v9, v4
	s_waitcnt lgkmcnt(0)
	v_add_f32_e32 v4, v4, v5
	ds_bpermute_b32 v5, v8, v4
	s_waitcnt lgkmcnt(0)
	v_add_f32_e32 v4, v4, v5
	v_fmamk_f32 v4, v4, 0x3c000000, v157
	v_cmp_gt_f32_e32 vcc, s2, v4
	v_mul_f32_e32 v5, 0x4f800000, v4
	s_nop 0
	v_cndmask_b32_e32 v4, v4, v5, vcc
	v_sqrt_f32_e32 v5, v4
	s_nop 0
	v_add_u32_e32 v82, -1, v5
	v_fma_f32 v98, -v82, v5, v4
	v_cmp_ge_f32_e64 s[4:5], 0, v98
	v_add_u32_e32 v98, 1, v5
	s_nop 0
	v_cndmask_b32_e64 v82, v5, v82, s[4:5]
	v_fma_f32 v5, -v98, v5, v4
	v_cmp_lt_f32_e64 s[4:5], 0, v5
	s_nop 1
	v_cndmask_b32_e64 v5, v82, v98, s[4:5]
	v_mul_f32_e32 v82, 0x37800000, v5
	v_cndmask_b32_e32 v5, v5, v82, vcc
	v_cmp_class_f32_e32 vcc, v4, v216
	s_nop 1
	v_cndmask_b32_e32 v4, v5, v4, vcc
	v_div_scale_f32 v5, s[0:1], v4, v4, s3
	v_rcp_f32_e32 v82, v5
	s_nop 0
	v_fma_f32 v98, -v5, v82, 1.0
	v_fmac_f32_e32 v82, v98, v82
	v_div_scale_f32 v98, vcc, s3, v4, s3
	v_mul_f32_e32 v112, v98, v82
	v_fma_f32 v113, -v5, v112, v98
	v_fmac_f32_e32 v112, v113, v82
	v_fma_f32 v5, -v5, v112, v98
	v_div_fmas_f32 v5, v5, v82, v112
	v_div_fixup_f32 v82, v5, v4, s3
	v_lshlrev_b64 v[4:5], 11, v[2:3]
	v_mul_f32_e32 v2, v96, v82
	v_mov_b32_e32 v96, v192
	v_lshl_add_u64 v[4:5], s[90:91], 0, v[4:5]
	v_lshl_add_u64 v[4:5], v[4:5], 0, s[26:27]
	v_lshl_add_u64 v[4:5], v[4:5], 0, v[0:1]
	s_nop 0
	v_mul_f32_e32 v2, v96, v2
	v_cvt_pk_bf16_f32 v2, v2, v1
	v_mov_b32_e32 v96, v193
	s_nop 0
	global_store_short v[4:5], v2, off
	v_mul_f32_e32 v2, v97, v82
	s_nop 0
	v_mul_f32_e32 v2, v96, v2
	v_cvt_pk_bf16_f32 v2, v2, v1
	global_store_short v[4:5], v2, off offset:64
	v_mul_f32_e32 v2, v81, v82
	v_mov_b32_e32 v81, v194
	s_nop 0
	v_mul_f32_e32 v2, v81, v2
	v_cvt_pk_bf16_f32 v2, v2, v1
	global_store_short v[4:5], v2, off offset:128
	v_mul_f32_e32 v2, v80, v82
	v_mov_b32_e32 v80, v195
	s_nop 0
	v_mul_f32_e32 v2, v2, v80
	v_cvt_pk_bf16_f32 v2, v2, v1
	global_store_short v[4:5], v2, off offset:192
	v_or_b32_e32 v2, 3, v227
	v_lshl_add_u32 v80, v2, 9, v13
	ds_read2_b32 v[4:5], v80 offset1:32
	v_or_b32_e32 v2, s21, v2
	v_or_b32_e32 v2, s8, v2
	s_waitcnt lgkmcnt(0)
	v_fma_f32 v96, v115, v153, -v4
	v_fma_f32 v97, v131, v153, -v5
	ds_read2_b32 v[4:5], v80 offset0:64 offset1:96
	v_mul_f32_e32 v82, v97, v97
	v_fmac_f32_e32 v82, v96, v96
	s_waitcnt lgkmcnt(0)
	v_fma_f32 v81, v99, v153, -v4
	v_fmac_f32_e32 v82, v81, v81
	v_fma_f32 v80, v83, v153, -v5
	v_fmac_f32_e32 v82, v80, v80
	ds_bpermute_b32 v4, v12, v82
	s_waitcnt lgkmcnt(0)
	v_add_f32_e32 v4, v82, v4
	ds_bpermute_b32 v5, v11, v4
	s_waitcnt lgkmcnt(0)
	v_add_f32_e32 v4, v4, v5
	ds_bpermute_b32 v5, v10, v4
	s_waitcnt lgkmcnt(0)
	v_add_f32_e32 v4, v4, v5
	ds_bpermute_b32 v5, v9, v4
	s_waitcnt lgkmcnt(0)
	v_add_f32_e32 v4, v4, v5
	ds_bpermute_b32 v5, v8, v4
	s_waitcnt lgkmcnt(0)
	v_add_f32_e32 v4, v4, v5
	v_fmamk_f32 v4, v4, 0x3c000000, v157
	v_cmp_gt_f32_e32 vcc, s2, v4
	v_mul_f32_e32 v5, 0x4f800000, v4
	s_nop 0
	v_cndmask_b32_e32 v4, v4, v5, vcc
	v_sqrt_f32_e32 v5, v4
	s_nop 0
	v_add_u32_e32 v82, -1, v5
	v_fma_f32 v83, -v82, v5, v4
	v_cmp_ge_f32_e64 s[4:5], 0, v83
	v_add_u32_e32 v83, 1, v5
	s_nop 0
	v_cndmask_b32_e64 v82, v5, v82, s[4:5]
	v_fma_f32 v5, -v83, v5, v4
	v_cmp_lt_f32_e64 s[4:5], 0, v5
	s_nop 1
	v_cndmask_b32_e64 v5, v82, v83, s[4:5]
	v_mul_f32_e32 v82, 0x37800000, v5
	v_cndmask_b32_e32 v5, v5, v82, vcc
	v_cmp_class_f32_e32 vcc, v4, v216
	s_nop 1
	v_cndmask_b32_e32 v4, v5, v4, vcc
	v_div_scale_f32 v5, s[0:1], v4, v4, s3
	v_rcp_f32_e32 v82, v5
	s_nop 0
	v_fma_f32 v83, -v5, v82, 1.0
	v_fmac_f32_e32 v82, v83, v82
	v_div_scale_f32 v83, vcc, s3, v4, s3
	v_mul_f32_e32 v98, v83, v82
	v_fma_f32 v99, -v5, v98, v83
	v_fmac_f32_e32 v98, v99, v82
	v_fma_f32 v5, -v5, v98, v83
	v_mov_b32_e32 v83, v192
	v_div_fmas_f32 v5, v5, v82, v98
	v_div_fixup_f32 v82, v5, v4, s3
	v_lshlrev_b64 v[4:5], 11, v[2:3]
	v_mul_f32_e32 v2, v96, v82
	v_lshl_add_u64 v[4:5], s[90:91], 0, v[4:5]
	v_lshl_add_u64 v[4:5], v[4:5], 0, s[26:27]
	v_lshl_add_u64 v[4:5], v[4:5], 0, v[0:1]
	s_nop 0
	v_mul_f32_e32 v2, v83, v2
	v_cvt_pk_bf16_f32 v2, v2, v1
	v_mov_b32_e32 v83, v193
	s_nop 0
	global_store_short v[4:5], v2, off
	v_mul_f32_e32 v2, v97, v82
	s_nop 0
	v_mul_f32_e32 v2, v83, v2
	v_cvt_pk_bf16_f32 v2, v2, v1
	global_store_short v[4:5], v2, off offset:64
	v_mul_f32_e32 v2, v81, v82
	v_mov_b32_e32 v81, v194
	s_nop 0
	v_mul_f32_e32 v2, v81, v2
	v_cvt_pk_bf16_f32 v2, v2, v1
	global_store_short v[4:5], v2, off offset:128
	v_mul_f32_e32 v2, v80, v82
	v_mov_b32_e32 v80, v195
	s_nop 0
	v_mul_f32_e32 v2, v2, v80
	v_cvt_pk_bf16_f32 v2, v2, v1
	global_store_short v[4:5], v2, off offset:192
	v_or_b32_e32 v2, 8, v227
	v_lshl_add_u32 v80, v2, 9, v13
	ds_read2_b32 v[4:5], v80 offset1:32
	v_or_b32_e32 v2, s21, v2
	v_or_b32_e32 v2, s8, v2
	s_waitcnt lgkmcnt(0)
	v_fma_f32 v83, v116, v152, -v4
	v_fma_f32 v96, v132, v152, -v5
	ds_read2_b32 v[4:5], v80 offset0:64 offset1:96
	v_mul_f32_e32 v82, v96, v96
	v_fmac_f32_e32 v82, v83, v83
	s_waitcnt lgkmcnt(0)
	v_fma_f32 v81, v100, v152, -v4
	v_fmac_f32_e32 v82, v81, v81
	v_fma_f32 v80, v84, v152, -v5
	v_fmac_f32_e32 v82, v80, v80
	ds_bpermute_b32 v4, v12, v82
	s_waitcnt lgkmcnt(0)
; __device__ __forceinline__ unsigned cvtpk(float lo, float hi) { unsigned r; asm volatile("v_cvt_pk_bf16_f32 %0, %1, %2" : "=v"(r) : "v"(lo), "v"(hi)); return r; }
; __device__ __forceinline__ float sx(float v, int mask, int lane) { return __int_as_float(__builtin_amdgcn_ds_bpermute((lane ^ mask) << 2, __float_as_int(v))); }
; __device__ __forceinline__ int crow(int r, int hi) { return (r & 3) + 8 * (r >> 2) + 4 * hi; }
;     __device__ __forceinline__ long qtok(int wid, int i) const { return (long)b * T + res + dil * (qs0 + 32 * wid + i); }
;     __device__ __forceinline__ long qtok(int wid, int i) const { return (long)b * T + 256 * qb + 32 * wid + i; }
;     __device__ __forceinline__ long qtok(int wid, int i) const { return (long)b * T + 128 * qb + 32 * (wid & 3) + i; }
; template <class Pol>
; __device__ __forceinline__ void attn_unit(const Pol& P, LAS unsigned char* lds, const Ptrs& X, bf16x8& pq0, bf16x8& pq1, bf16x8& pq2, bf16x8& pq3, bf16x8& pk_, bf16x8& pv_, bool have, const Pol& Pn, bool hasn) {
;     ...
;         if (wid < 4) {
; #pragma unroll
;             for (int r = 0; r < 16; ++r) { const int row = 32 * wid + crow(r, hi); float s = 0.f;
; #pragma unroll
;                 for (int d = 0; d < NB; ++d) { const float y = o[d][r] * rli[r] - XB[row * 128 + d * 32 + r32]; o[d][r] = y; s += y * y; }
;                 s += sx(s, 1, lane); s += sx(s, 2, lane); s += sx(s, 4, lane); s += sx(s, 8, lane); s += sx(s, 16, lane);
;                 const float rs = (1.0f - LAM_INIT) / sqrtf(s * (1.0f / 128.f) + SUBLN_EPS);
;                 const long tok = P.qtok(wid, crow(r, hi));
; #pragma unroll
;                 for (int d = 0; d < NB; ++d) X.att[tok * D + P.h * 128 + d * 32 + r32] = (bf16_t)(cvtpk(o[d][r] * rs * X.subln[d * 32 + r32], 0.f) & 0xffffu); }
;         }
	v_add_f32_e32 v4, v82, v4
	ds_bpermute_b32 v5, v11, v4
	s_waitcnt lgkmcnt(0)
	v_add_f32_e32 v4, v4, v5
	ds_bpermute_b32 v5, v10, v4
	s_waitcnt lgkmcnt(0)
	v_add_f32_e32 v4, v4, v5
	ds_bpermute_b32 v5, v9, v4
	s_waitcnt lgkmcnt(0)
	v_add_f32_e32 v4, v4, v5
	ds_bpermute_b32 v5, v8, v4
	s_waitcnt lgkmcnt(0)
	v_add_f32_e32 v4, v4, v5
	v_fmamk_f32 v4, v4, 0x3c000000, v157
	v_cmp_gt_f32_e32 vcc, s2, v4
	v_mul_f32_e32 v5, 0x4f800000, v4
	s_nop 0
	v_cndmask_b32_e32 v4, v4, v5, vcc
	v_sqrt_f32_e32 v5, v4
	s_nop 0
	v_add_u32_e32 v82, -1, v5
	v_fma_f32 v84, -v82, v5, v4
	v_cmp_ge_f32_e64 s[4:5], 0, v84
	v_add_u32_e32 v84, 1, v5
	s_nop 0
	v_cndmask_b32_e64 v82, v5, v82, s[4:5]
	v_fma_f32 v5, -v84, v5, v4
	v_cmp_lt_f32_e64 s[4:5], 0, v5
	s_nop 1
	v_cndmask_b32_e64 v5, v82, v84, s[4:5]
	v_mul_f32_e32 v82, 0x37800000, v5
	v_cndmask_b32_e32 v5, v5, v82, vcc
	v_cmp_class_f32_e32 vcc, v4, v216
	s_nop 1
	v_cndmask_b32_e32 v4, v5, v4, vcc
	v_div_scale_f32 v5, s[0:1], v4, v4, s3
	v_rcp_f32_e32 v82, v5
	s_nop 0
	v_fma_f32 v84, -v5, v82, 1.0
	v_fmac_f32_e32 v82, v84, v82
	v_div_scale_f32 v84, vcc, s3, v4, s3
	v_mul_f32_e32 v97, v84, v82
	v_fma_f32 v98, -v5, v97, v84
	v_fmac_f32_e32 v97, v98, v82
	v_fma_f32 v5, -v5, v97, v84
	v_div_fmas_f32 v5, v5, v82, v97
	v_div_fixup_f32 v82, v5, v4, s3
	v_lshlrev_b64 v[4:5], 11, v[2:3]
	v_mul_f32_e32 v2, v83, v82
	v_mov_b32_e32 v83, v192
	v_lshl_add_u64 v[4:5], s[90:91], 0, v[4:5]
	v_lshl_add_u64 v[4:5], v[4:5], 0, s[26:27]
	v_lshl_add_u64 v[4:5], v[4:5], 0, v[0:1]
	s_nop 0
	v_mul_f32_e32 v2, v83, v2
	v_cvt_pk_bf16_f32 v2, v2, v1
	v_mov_b32_e32 v83, v193
	s_nop 0
	global_store_short v[4:5], v2, off
	v_mul_f32_e32 v2, v96, v82
	s_nop 0
	v_mul_f32_e32 v2, v83, v2
	v_cvt_pk_bf16_f32 v2, v2, v1
	global_store_short v[4:5], v2, off offset:64
	v_mul_f32_e32 v2, v81, v82
	v_mov_b32_e32 v81, v194
	s_nop 0
	v_mul_f32_e32 v2, v81, v2
	v_cvt_pk_bf16_f32 v2, v2, v1
	global_store_short v[4:5], v2, off offset:128
	v_mul_f32_e32 v2, v80, v82
	v_mov_b32_e32 v80, v195
	s_nop 0
	v_mul_f32_e32 v2, v2, v80
	v_cvt_pk_bf16_f32 v2, v2, v1
	global_store_short v[4:5], v2, off offset:192
	v_or_b32_e32 v2, 9, v227
	v_lshl_add_u32 v80, v2, 9, v13
	ds_read2_b32 v[4:5], v80 offset1:32
	v_or_b32_e32 v2, s21, v2
	v_or_b32_e32 v2, s8, v2
	s_waitcnt lgkmcnt(0)
	v_fma_f32 v83, v117, v151, -v4
	v_fma_f32 v84, v133, v151, -v5
	ds_read2_b32 v[4:5], v80 offset0:64 offset1:96
	v_mul_f32_e32 v82, v84, v84
	v_fmac_f32_e32 v82, v83, v83
	s_waitcnt lgkmcnt(0)
	v_fma_f32 v81, v101, v151, -v4
	v_fmac_f32_e32 v82, v81, v81
	v_fma_f32 v80, v85, v151, -v5
	v_fmac_f32_e32 v82, v80, v80
	ds_bpermute_b32 v4, v12, v82
	s_waitcnt lgkmcnt(0)
	v_add_f32_e32 v4, v82, v4
	ds_bpermute_b32 v5, v11, v4
	s_waitcnt lgkmcnt(0)
	v_add_f32_e32 v4, v4, v5
	ds_bpermute_b32 v5, v10, v4
	s_waitcnt lgkmcnt(0)
	v_add_f32_e32 v4, v4, v5
	ds_bpermute_b32 v5, v9, v4
	s_waitcnt lgkmcnt(0)
	v_add_f32_e32 v4, v4, v5
	ds_bpermute_b32 v5, v8, v4
	s_waitcnt lgkmcnt(0)
	v_add_f32_e32 v4, v4, v5
	v_fmamk_f32 v4, v4, 0x3c000000, v157
	v_cmp_gt_f32_e32 vcc, s2, v4
	v_mul_f32_e32 v5, 0x4f800000, v4
	s_nop 0
	v_cndmask_b32_e32 v4, v4, v5, vcc
	v_sqrt_f32_e32 v5, v4
	s_nop 0
	v_add_u32_e32 v82, -1, v5
	v_fma_f32 v85, -v82, v5, v4
	v_cmp_ge_f32_e64 s[4:5], 0, v85
	v_add_u32_e32 v85, 1, v5
	s_nop 0
	v_cndmask_b32_e64 v82, v5, v82, s[4:5]
	v_fma_f32 v5, -v85, v5, v4
	v_cmp_lt_f32_e64 s[4:5], 0, v5
	s_nop 1
	v_cndmask_b32_e64 v5, v82, v85, s[4:5]
	v_mul_f32_e32 v82, 0x37800000, v5
	v_cndmask_b32_e32 v5, v5, v82, vcc
	v_cmp_class_f32_e32 vcc, v4, v216
	s_nop 1
	v_cndmask_b32_e32 v4, v5, v4, vcc
	v_div_scale_f32 v5, s[0:1], v4, v4, s3
	v_rcp_f32_e32 v82, v5
	s_nop 0
	v_fma_f32 v85, -v5, v82, 1.0
	v_fmac_f32_e32 v82, v85, v82
	v_div_scale_f32 v85, vcc, s3, v4, s3
	v_mul_f32_e32 v96, v85, v82
	v_fma_f32 v97, -v5, v96, v85
	v_fmac_f32_e32 v96, v97, v82
	v_fma_f32 v5, -v5, v96, v85
	v_div_fmas_f32 v5, v5, v82, v96
	v_div_fixup_f32 v82, v5, v4, s3
	v_lshlrev_b64 v[4:5], 11, v[2:3]
	v_mul_f32_e32 v2, v83, v82
	v_mov_b32_e32 v83, v192
	v_lshl_add_u64 v[4:5], s[90:91], 0, v[4:5]
	v_lshl_add_u64 v[4:5], v[4:5], 0, s[26:27]
	v_lshl_add_u64 v[4:5], v[4:5], 0, v[0:1]
	s_nop 0
	v_mul_f32_e32 v2, v83, v2
	v_cvt_pk_bf16_f32 v2, v2, v1
	v_mov_b32_e32 v83, v193
	s_nop 0
	global_store_short v[4:5], v2, off
	v_mul_f32_e32 v2, v84, v82
	s_nop 0
	v_mul_f32_e32 v2, v83, v2
	v_cvt_pk_bf16_f32 v2, v2, v1
	global_store_short v[4:5], v2, off offset:64
	v_mul_f32_e32 v2, v81, v82
	v_mov_b32_e32 v81, v194
	s_nop 0
	v_mul_f32_e32 v2, v81, v2
	v_cvt_pk_bf16_f32 v2, v2, v1
	global_store_short v[4:5], v2, off offset:128
	v_mul_f32_e32 v2, v80, v82
	v_mov_b32_e32 v80, v195
	s_nop 0
	v_mul_f32_e32 v2, v2, v80
	v_cvt_pk_bf16_f32 v2, v2, v1
	global_store_short v[4:5], v2, off offset:192
	v_or_b32_e32 v2, 10, v227
	v_lshl_add_u32 v80, v2, 9, v13
	ds_read2_b32 v[4:5], v80 offset1:32
	v_or_b32_e32 v2, s21, v2
	v_or_b32_e32 v2, s8, v2
	s_waitcnt lgkmcnt(0)
	v_fma_f32 v83, v118, v150, -v4
	v_fma_f32 v84, v134, v150, -v5
	ds_read2_b32 v[4:5], v80 offset0:64 offset1:96
	v_mul_f32_e32 v82, v84, v84
	v_fmac_f32_e32 v82, v83, v83
	s_waitcnt lgkmcnt(0)
	v_fma_f32 v81, v102, v150, -v4
	v_fmac_f32_e32 v82, v81, v81
	v_fma_f32 v80, v86, v150, -v5
	v_fmac_f32_e32 v82, v80, v80
	ds_bpermute_b32 v4, v12, v82
	s_waitcnt lgkmcnt(0)
	v_add_f32_e32 v4, v82, v4
	ds_bpermute_b32 v5, v11, v4
	s_waitcnt lgkmcnt(0)
	v_add_f32_e32 v4, v4, v5
	ds_bpermute_b32 v5, v10, v4
	s_waitcnt lgkmcnt(0)
	v_add_f32_e32 v4, v4, v5
	ds_bpermute_b32 v5, v9, v4
	s_waitcnt lgkmcnt(0)
	v_add_f32_e32 v4, v4, v5
	ds_bpermute_b32 v5, v8, v4
	s_waitcnt lgkmcnt(0)
; __device__ __forceinline__ unsigned cvtpk(float lo, float hi) { unsigned r; asm volatile("v_cvt_pk_bf16_f32 %0, %1, %2" : "=v"(r) : "v"(lo), "v"(hi)); return r; }
; __device__ __forceinline__ float sx(float v, int mask, int lane) { return __int_as_float(__builtin_amdgcn_ds_bpermute((lane ^ mask) << 2, __float_as_int(v))); }
; __device__ __forceinline__ int crow(int r, int hi) { return (r & 3) + 8 * (r >> 2) + 4 * hi; }
;     __device__ __forceinline__ long qtok(int wid, int i) const { return (long)b * T + res + dil * (qs0 + 32 * wid + i); }
;     __device__ __forceinline__ long qtok(int wid, int i) const { return (long)b * T + 256 * qb + 32 * wid + i; }
;     __device__ __forceinline__ long qtok(int wid, int i) const { return (long)b * T + 128 * qb + 32 * (wid & 3) + i; }
; template <class Pol>
; __device__ __forceinline__ void attn_unit(const Pol& P, LAS unsigned char* lds, const Ptrs& X, bf16x8& pq0, bf16x8& pq1, bf16x8& pq2, bf16x8& pq3, bf16x8& pk_, bf16x8& pv_, bool have, const Pol& Pn, bool hasn) {
;     ...
;         if (wid < 4) {
; #pragma unroll
;             for (int r = 0; r < 16; ++r) { const int row = 32 * wid + crow(r, hi); float s = 0.f;
; #pragma unroll
;                 for (int d = 0; d < NB; ++d) { const float y = o[d][r] * rli[r] - XB[row * 128 + d * 32 + r32]; o[d][r] = y; s += y * y; }
;                 s += sx(s, 1, lane); s += sx(s, 2, lane); s += sx(s, 4, lane); s += sx(s, 8, lane); s += sx(s, 16, lane);
;                 const float rs = (1.0f - LAM_INIT) / sqrtf(s * (1.0f / 128.f) + SUBLN_EPS);
;                 const long tok = P.qtok(wid, crow(r, hi));
; #pragma unroll
;                 for (int d = 0; d < NB; ++d) X.att[tok * D + P.h * 128 + d * 32 + r32] = (bf16_t)(cvtpk(o[d][r] * rs * X.subln[d * 32 + r32], 0.f) & 0xffffu); }
;         }
	v_add_f32_e32 v4, v4, v5
	v_fmamk_f32 v4, v4, 0x3c000000, v157
	v_cmp_gt_f32_e32 vcc, s2, v4
	v_mul_f32_e32 v5, 0x4f800000, v4
	s_nop 0
	v_cndmask_b32_e32 v4, v4, v5, vcc
	v_sqrt_f32_e32 v5, v4
	s_nop 0
	v_add_u32_e32 v82, -1, v5
	v_fma_f32 v85, -v82, v5, v4
	v_cmp_ge_f32_e64 s[4:5], 0, v85
	v_add_u32_e32 v85, 1, v5
	s_nop 0
	v_cndmask_b32_e64 v82, v5, v82, s[4:5]
	v_fma_f32 v5, -v85, v5, v4
	v_cmp_lt_f32_e64 s[4:5], 0, v5
	s_nop 1
	v_cndmask_b32_e64 v5, v82, v85, s[4:5]
	v_mul_f32_e32 v82, 0x37800000, v5
	v_cndmask_b32_e32 v5, v5, v82, vcc
	v_cmp_class_f32_e32 vcc, v4, v216
	s_nop 1
	v_cndmask_b32_e32 v4, v5, v4, vcc
	v_div_scale_f32 v5, s[0:1], v4, v4, s3
	v_rcp_f32_e32 v82, v5
	s_nop 0
	v_fma_f32 v85, -v5, v82, 1.0
	v_fmac_f32_e32 v82, v85, v82
	v_div_scale_f32 v85, vcc, s3, v4, s3
	v_mul_f32_e32 v86, v85, v82
	v_fma_f32 v96, -v5, v86, v85
	v_fmac_f32_e32 v86, v96, v82
	v_fma_f32 v5, -v5, v86, v85
	v_div_fmas_f32 v5, v5, v82, v86
	v_div_fixup_f32 v82, v5, v4, s3
	v_lshlrev_b64 v[4:5], 11, v[2:3]
	v_mul_f32_e32 v2, v83, v82
	v_mov_b32_e32 v83, v192
	v_lshl_add_u64 v[4:5], s[90:91], 0, v[4:5]
	v_lshl_add_u64 v[4:5], v[4:5], 0, s[26:27]
	v_lshl_add_u64 v[4:5], v[4:5], 0, v[0:1]
	s_nop 0
	v_mul_f32_e32 v2, v83, v2
	v_cvt_pk_bf16_f32 v2, v2, v1
	v_mov_b32_e32 v83, v193
	s_nop 0
	global_store_short v[4:5], v2, off
	v_mul_f32_e32 v2, v84, v82
	s_nop 0
	v_mul_f32_e32 v2, v83, v2
	v_cvt_pk_bf16_f32 v2, v2, v1
	global_store_short v[4:5], v2, off offset:64
	v_mul_f32_e32 v2, v81, v82
	v_mov_b32_e32 v81, v194
	s_nop 0
	v_mul_f32_e32 v2, v81, v2
	v_cvt_pk_bf16_f32 v2, v2, v1
	global_store_short v[4:5], v2, off offset:128
	v_mul_f32_e32 v2, v80, v82
	v_mov_b32_e32 v80, v195
	s_nop 0
	v_mul_f32_e32 v2, v2, v80
	v_cvt_pk_bf16_f32 v2, v2, v1
	global_store_short v[4:5], v2, off offset:192
	v_or_b32_e32 v2, 11, v227
	v_lshl_add_u32 v80, v2, 9, v13
	ds_read2_b32 v[4:5], v80 offset1:32
	v_or_b32_e32 v2, s21, v2
	v_or_b32_e32 v2, s8, v2
	s_waitcnt lgkmcnt(0)
	v_fma_f32 v83, v119, v149, -v4
	v_fma_f32 v84, v135, v149, -v5
	ds_read2_b32 v[4:5], v80 offset0:64 offset1:96
	v_mul_f32_e32 v82, v84, v84
	v_fmac_f32_e32 v82, v83, v83
	s_waitcnt lgkmcnt(0)
	v_fma_f32 v81, v103, v149, -v4
	v_fmac_f32_e32 v82, v81, v81
	v_fma_f32 v80, v87, v149, -v5
	v_fmac_f32_e32 v82, v80, v80
	ds_bpermute_b32 v4, v12, v82
	s_waitcnt lgkmcnt(0)
	v_add_f32_e32 v4, v82, v4
	ds_bpermute_b32 v5, v11, v4
	s_waitcnt lgkmcnt(0)
	v_add_f32_e32 v4, v4, v5
	ds_bpermute_b32 v5, v10, v4
	s_waitcnt lgkmcnt(0)
	v_add_f32_e32 v4, v4, v5
	ds_bpermute_b32 v5, v9, v4
	s_waitcnt lgkmcnt(0)
	v_add_f32_e32 v4, v4, v5
	ds_bpermute_b32 v5, v8, v4
	s_waitcnt lgkmcnt(0)
	v_add_f32_e32 v4, v4, v5
	v_fmamk_f32 v4, v4, 0x3c000000, v157
	v_cmp_gt_f32_e32 vcc, s2, v4
	v_mul_f32_e32 v5, 0x4f800000, v4
	s_nop 0
	v_cndmask_b32_e32 v4, v4, v5, vcc
	v_sqrt_f32_e32 v5, v4
	s_nop 0
	v_add_u32_e32 v82, -1, v5
	v_fma_f32 v85, -v82, v5, v4
	v_cmp_ge_f32_e64 s[4:5], 0, v85
	v_add_u32_e32 v85, 1, v5
	s_nop 0
	v_cndmask_b32_e64 v82, v5, v82, s[4:5]
	v_fma_f32 v5, -v85, v5, v4
	v_cmp_lt_f32_e64 s[4:5], 0, v5
	s_nop 1
	v_cndmask_b32_e64 v5, v82, v85, s[4:5]
	v_mul_f32_e32 v82, 0x37800000, v5
	v_cndmask_b32_e32 v5, v5, v82, vcc
	v_cmp_class_f32_e32 vcc, v4, v216
	s_nop 1
	v_cndmask_b32_e32 v4, v5, v4, vcc
	v_div_scale_f32 v5, s[0:1], v4, v4, s3
	v_rcp_f32_e32 v82, v5
	s_nop 0
	v_fma_f32 v85, -v5, v82, 1.0
	v_fmac_f32_e32 v82, v85, v82
	v_div_scale_f32 v85, vcc, s3, v4, s3
	v_mul_f32_e32 v86, v85, v82
	v_fma_f32 v87, -v5, v86, v85
	v_fmac_f32_e32 v86, v87, v82
	v_fma_f32 v5, -v5, v86, v85
	v_div_fmas_f32 v5, v5, v82, v86
	v_div_fixup_f32 v82, v5, v4, s3
	v_lshlrev_b64 v[4:5], 11, v[2:3]
	v_mul_f32_e32 v2, v83, v82
	v_mov_b32_e32 v83, v192
	v_lshl_add_u64 v[4:5], s[90:91], 0, v[4:5]
	v_lshl_add_u64 v[4:5], v[4:5], 0, s[26:27]
	v_lshl_add_u64 v[4:5], v[4:5], 0, v[0:1]
	s_nop 0
	v_mul_f32_e32 v2, v83, v2
	v_cvt_pk_bf16_f32 v2, v2, v1
	v_mov_b32_e32 v83, v193
	s_nop 0
	global_store_short v[4:5], v2, off
	v_mul_f32_e32 v2, v84, v82
	s_nop 0
	v_mul_f32_e32 v2, v83, v2
	v_cvt_pk_bf16_f32 v2, v2, v1
	global_store_short v[4:5], v2, off offset:64
	v_mul_f32_e32 v2, v81, v82
	v_mov_b32_e32 v81, v194
	s_nop 0
	v_mul_f32_e32 v2, v81, v2
	v_cvt_pk_bf16_f32 v2, v2, v1
	global_store_short v[4:5], v2, off offset:128
	v_mul_f32_e32 v2, v80, v82
	v_mov_b32_e32 v80, v195
	s_nop 0
	v_mul_f32_e32 v2, v2, v80
	v_cvt_pk_bf16_f32 v2, v2, v1
	global_store_short v[4:5], v2, off offset:192
	v_or_b32_e32 v2, 16, v227
	v_lshl_add_u32 v80, v2, 9, v13
	ds_read2_b32 v[4:5], v80 offset1:32
	v_or_b32_e32 v2, s21, v2
	v_or_b32_e32 v2, s8, v2
	s_waitcnt lgkmcnt(0)
	v_fma_f32 v83, v120, v148, -v4
	v_fma_f32 v84, v136, v148, -v5
	ds_read2_b32 v[4:5], v80 offset0:64 offset1:96
	v_mul_f32_e32 v82, v84, v84
	v_fmac_f32_e32 v82, v83, v83
	s_waitcnt lgkmcnt(0)
	v_fma_f32 v81, v104, v148, -v4
	v_fmac_f32_e32 v82, v81, v81
	v_fma_f32 v80, v88, v148, -v5
	v_fmac_f32_e32 v82, v80, v80
	ds_bpermute_b32 v4, v12, v82
	s_waitcnt lgkmcnt(0)
	v_add_f32_e32 v4, v82, v4
	ds_bpermute_b32 v5, v11, v4
	s_waitcnt lgkmcnt(0)
	v_add_f32_e32 v4, v4, v5
	ds_bpermute_b32 v5, v10, v4
	s_waitcnt lgkmcnt(0)
	v_add_f32_e32 v4, v4, v5
	ds_bpermute_b32 v5, v9, v4
	s_waitcnt lgkmcnt(0)
	v_add_f32_e32 v4, v4, v5
	ds_bpermute_b32 v5, v8, v4
	s_waitcnt lgkmcnt(0)
; __device__ __forceinline__ unsigned cvtpk(float lo, float hi) { unsigned r; asm volatile("v_cvt_pk_bf16_f32 %0, %1, %2" : "=v"(r) : "v"(lo), "v"(hi)); return r; }
; __device__ __forceinline__ float sx(float v, int mask, int lane) { return __int_as_float(__builtin_amdgcn_ds_bpermute((lane ^ mask) << 2, __float_as_int(v))); }
; __device__ __forceinline__ int crow(int r, int hi) { return (r & 3) + 8 * (r >> 2) + 4 * hi; }
;     __device__ __forceinline__ long qtok(int wid, int i) const { return (long)b * T + res + dil * (qs0 + 32 * wid + i); }
;     __device__ __forceinline__ long qtok(int wid, int i) const { return (long)b * T + 256 * qb + 32 * wid + i; }
;     __device__ __forceinline__ long qtok(int wid, int i) const { return (long)b * T + 128 * qb + 32 * (wid & 3) + i; }
; template <class Pol>
; __device__ __forceinline__ void attn_unit(const Pol& P, LAS unsigned char* lds, const Ptrs& X, bf16x8& pq0, bf16x8& pq1, bf16x8& pq2, bf16x8& pq3, bf16x8& pk_, bf16x8& pv_, bool have, const Pol& Pn, bool hasn) {
;     ...
;         if (wid < 4) {
; #pragma unroll
;             for (int r = 0; r < 16; ++r) { const int row = 32 * wid + crow(r, hi); float s = 0.f;
; #pragma unroll
;                 for (int d = 0; d < NB; ++d) { const float y = o[d][r] * rli[r] - XB[row * 128 + d * 32 + r32]; o[d][r] = y; s += y * y; }
;                 s += sx(s, 1, lane); s += sx(s, 2, lane); s += sx(s, 4, lane); s += sx(s, 8, lane); s += sx(s, 16, lane);
;                 const float rs = (1.0f - LAM_INIT) / sqrtf(s * (1.0f / 128.f) + SUBLN_EPS);
;                 const long tok = P.qtok(wid, crow(r, hi));
; #pragma unroll
;                 for (int d = 0; d < NB; ++d) X.att[tok * D + P.h * 128 + d * 32 + r32] = (bf16_t)(cvtpk(o[d][r] * rs * X.subln[d * 32 + r32], 0.f) & 0xffffu); }
;         }
	v_add_f32_e32 v4, v4, v5
	v_fmamk_f32 v4, v4, 0x3c000000, v157
	v_cmp_gt_f32_e32 vcc, s2, v4
	v_mul_f32_e32 v5, 0x4f800000, v4
	s_nop 0
	v_cndmask_b32_e32 v4, v4, v5, vcc
	v_sqrt_f32_e32 v5, v4
	s_nop 0
	v_add_u32_e32 v82, -1, v5
	v_fma_f32 v85, -v82, v5, v4
	v_cmp_ge_f32_e64 s[4:5], 0, v85
	v_add_u32_e32 v85, 1, v5
	s_nop 0
	v_cndmask_b32_e64 v82, v5, v82, s[4:5]
	v_fma_f32 v5, -v85, v5, v4
	v_cmp_lt_f32_e64 s[4:5], 0, v5
	s_nop 1
	v_cndmask_b32_e64 v5, v82, v85, s[4:5]
	v_mul_f32_e32 v82, 0x37800000, v5
	v_cndmask_b32_e32 v5, v5, v82, vcc
	v_cmp_class_f32_e32 vcc, v4, v216
	s_nop 1
	v_cndmask_b32_e32 v4, v5, v4, vcc
	v_div_scale_f32 v5, s[0:1], v4, v4, s3
	v_rcp_f32_e32 v82, v5
	s_nop 0
	v_fma_f32 v85, -v5, v82, 1.0
	v_fmac_f32_e32 v82, v85, v82
	v_div_scale_f32 v85, vcc, s3, v4, s3
	v_mul_f32_e32 v86, v85, v82
	v_fma_f32 v87, -v5, v86, v85
	v_fmac_f32_e32 v86, v87, v82
	v_fma_f32 v5, -v5, v86, v85
	v_div_fmas_f32 v5, v5, v82, v86
	v_div_fixup_f32 v82, v5, v4, s3
	v_lshlrev_b64 v[4:5], 11, v[2:3]
	v_mul_f32_e32 v2, v83, v82
	v_mov_b32_e32 v83, v192
	v_lshl_add_u64 v[4:5], s[90:91], 0, v[4:5]
	v_lshl_add_u64 v[4:5], v[4:5], 0, s[26:27]
	v_lshl_add_u64 v[4:5], v[4:5], 0, v[0:1]
	s_nop 0
	v_mul_f32_e32 v2, v83, v2
	v_cvt_pk_bf16_f32 v2, v2, v1
	v_mov_b32_e32 v83, v193
	s_nop 0
	global_store_short v[4:5], v2, off
	v_mul_f32_e32 v2, v84, v82
	s_nop 0
	v_mul_f32_e32 v2, v83, v2
	v_cvt_pk_bf16_f32 v2, v2, v1
	global_store_short v[4:5], v2, off offset:64
	v_mul_f32_e32 v2, v81, v82
	v_mov_b32_e32 v81, v194
	s_nop 0
	v_mul_f32_e32 v2, v81, v2
	v_cvt_pk_bf16_f32 v2, v2, v1
	global_store_short v[4:5], v2, off offset:128
	v_mul_f32_e32 v2, v80, v82
	v_mov_b32_e32 v80, v195
	s_nop 0
	v_mul_f32_e32 v2, v2, v80
	v_cvt_pk_bf16_f32 v2, v2, v1
	global_store_short v[4:5], v2, off offset:192
	v_or_b32_e32 v2, 17, v227
	v_lshl_add_u32 v80, v2, 9, v13
	ds_read2_b32 v[4:5], v80 offset1:32
	v_or_b32_e32 v2, s21, v2
	v_or_b32_e32 v2, s8, v2
	s_waitcnt lgkmcnt(0)
	v_fma_f32 v83, v121, v147, -v4
	v_fma_f32 v84, v137, v147, -v5
	ds_read2_b32 v[4:5], v80 offset0:64 offset1:96
	v_mul_f32_e32 v82, v84, v84
	v_fmac_f32_e32 v82, v83, v83
	s_waitcnt lgkmcnt(0)
	v_fma_f32 v81, v105, v147, -v4
	v_fmac_f32_e32 v82, v81, v81
	v_fma_f32 v80, v89, v147, -v5
	v_fmac_f32_e32 v82, v80, v80
	ds_bpermute_b32 v4, v12, v82
	s_waitcnt lgkmcnt(0)
	v_add_f32_e32 v4, v82, v4
	ds_bpermute_b32 v5, v11, v4
	s_waitcnt lgkmcnt(0)
	v_add_f32_e32 v4, v4, v5
	ds_bpermute_b32 v5, v10, v4
	s_waitcnt lgkmcnt(0)
	v_add_f32_e32 v4, v4, v5
	ds_bpermute_b32 v5, v9, v4
	s_waitcnt lgkmcnt(0)
	v_add_f32_e32 v4, v4, v5
	ds_bpermute_b32 v5, v8, v4
	s_waitcnt lgkmcnt(0)
	v_add_f32_e32 v4, v4, v5
	v_fmamk_f32 v4, v4, 0x3c000000, v157
	v_cmp_gt_f32_e32 vcc, s2, v4
	v_mul_f32_e32 v5, 0x4f800000, v4
	s_nop 0
	v_cndmask_b32_e32 v4, v4, v5, vcc
	v_sqrt_f32_e32 v5, v4
	s_nop 0
	v_add_u32_e32 v82, -1, v5
	v_fma_f32 v85, -v82, v5, v4
	v_cmp_ge_f32_e64 s[4:5], 0, v85
	v_add_u32_e32 v85, 1, v5
	s_nop 0
	v_cndmask_b32_e64 v82, v5, v82, s[4:5]
	v_fma_f32 v5, -v85, v5, v4
	v_cmp_lt_f32_e64 s[4:5], 0, v5
	s_nop 1
	v_cndmask_b32_e64 v5, v82, v85, s[4:5]
	v_mul_f32_e32 v82, 0x37800000, v5
	v_cndmask_b32_e32 v5, v5, v82, vcc
	v_cmp_class_f32_e32 vcc, v4, v216
	s_nop 1
	v_cndmask_b32_e32 v4, v5, v4, vcc
	v_div_scale_f32 v5, s[0:1], v4, v4, s3
	v_rcp_f32_e32 v82, v5
	s_nop 0
	v_fma_f32 v85, -v5, v82, 1.0
	v_fmac_f32_e32 v82, v85, v82
	v_div_scale_f32 v85, vcc, s3, v4, s3
	v_mul_f32_e32 v86, v85, v82
	v_fma_f32 v87, -v5, v86, v85
	v_fmac_f32_e32 v86, v87, v82
	v_fma_f32 v5, -v5, v86, v85
	v_div_fmas_f32 v5, v5, v82, v86
	v_div_fixup_f32 v82, v5, v4, s3
	v_lshlrev_b64 v[4:5], 11, v[2:3]
	v_mul_f32_e32 v2, v83, v82
	v_mov_b32_e32 v83, v192
	v_lshl_add_u64 v[4:5], s[90:91], 0, v[4:5]
	v_lshl_add_u64 v[4:5], v[4:5], 0, s[26:27]
	v_lshl_add_u64 v[4:5], v[4:5], 0, v[0:1]
	s_nop 0
	v_mul_f32_e32 v2, v83, v2
	v_cvt_pk_bf16_f32 v2, v2, v1
	v_mov_b32_e32 v83, v193
	s_nop 0
	global_store_short v[4:5], v2, off
	v_mul_f32_e32 v2, v84, v82
	s_nop 0
	v_mul_f32_e32 v2, v83, v2
	v_cvt_pk_bf16_f32 v2, v2, v1
	global_store_short v[4:5], v2, off offset:64
	v_mul_f32_e32 v2, v81, v82
	v_mov_b32_e32 v81, v194
	s_nop 0
	v_mul_f32_e32 v2, v81, v2
	v_cvt_pk_bf16_f32 v2, v2, v1
	global_store_short v[4:5], v2, off offset:128
	v_mul_f32_e32 v2, v80, v82
	v_mov_b32_e32 v80, v195
	s_nop 0
	v_mul_f32_e32 v2, v2, v80
	v_cvt_pk_bf16_f32 v2, v2, v1
	global_store_short v[4:5], v2, off offset:192
	v_or_b32_e32 v2, 18, v227
	v_lshl_add_u32 v80, v2, 9, v13
	ds_read2_b32 v[4:5], v80 offset1:32
	v_or_b32_e32 v2, s21, v2
	v_or_b32_e32 v2, s8, v2
	s_waitcnt lgkmcnt(0)
	v_fma_f32 v83, v122, v146, -v4
	v_fma_f32 v84, v138, v146, -v5
	ds_read2_b32 v[4:5], v80 offset0:64 offset1:96
	v_mul_f32_e32 v82, v84, v84
	v_fmac_f32_e32 v82, v83, v83
	s_waitcnt lgkmcnt(0)
	v_fma_f32 v81, v106, v146, -v4
	v_fmac_f32_e32 v82, v81, v81
	v_fma_f32 v80, v90, v146, -v5
	v_fmac_f32_e32 v82, v80, v80
	ds_bpermute_b32 v4, v12, v82
	s_waitcnt lgkmcnt(0)
	v_add_f32_e32 v4, v82, v4
	ds_bpermute_b32 v5, v11, v4
	s_waitcnt lgkmcnt(0)
	v_add_f32_e32 v4, v4, v5
	ds_bpermute_b32 v5, v10, v4
	s_waitcnt lgkmcnt(0)
	v_add_f32_e32 v4, v4, v5
	ds_bpermute_b32 v5, v9, v4
	s_waitcnt lgkmcnt(0)
	v_add_f32_e32 v4, v4, v5
	ds_bpermute_b32 v5, v8, v4
	s_waitcnt lgkmcnt(0)
; __device__ __forceinline__ unsigned cvtpk(float lo, float hi) { unsigned r; asm volatile("v_cvt_pk_bf16_f32 %0, %1, %2" : "=v"(r) : "v"(lo), "v"(hi)); return r; }
; __device__ __forceinline__ float sx(float v, int mask, int lane) { return __int_as_float(__builtin_amdgcn_ds_bpermute((lane ^ mask) << 2, __float_as_int(v))); }
; __device__ __forceinline__ int crow(int r, int hi) { return (r & 3) + 8 * (r >> 2) + 4 * hi; }
;     __device__ __forceinline__ long qtok(int wid, int i) const { return (long)b * T + res + dil * (qs0 + 32 * wid + i); }
;     __device__ __forceinline__ long qtok(int wid, int i) const { return (long)b * T + 256 * qb + 32 * wid + i; }
;     __device__ __forceinline__ long qtok(int wid, int i) const { return (long)b * T + 128 * qb + 32 * (wid & 3) + i; }
; template <class Pol>
; __device__ __forceinline__ void attn_unit(const Pol& P, LAS unsigned char* lds, const Ptrs& X, bf16x8& pq0, bf16x8& pq1, bf16x8& pq2, bf16x8& pq3, bf16x8& pk_, bf16x8& pv_, bool have, const Pol& Pn, bool hasn) {
;     ...
;         if (wid < 4) {
; #pragma unroll
;             for (int r = 0; r < 16; ++r) { const int row = 32 * wid + crow(r, hi); float s = 0.f;
; #pragma unroll
;                 for (int d = 0; d < NB; ++d) { const float y = o[d][r] * rli[r] - XB[row * 128 + d * 32 + r32]; o[d][r] = y; s += y * y; }
;                 s += sx(s, 1, lane); s += sx(s, 2, lane); s += sx(s, 4, lane); s += sx(s, 8, lane); s += sx(s, 16, lane);
;                 const float rs = (1.0f - LAM_INIT) / sqrtf(s * (1.0f / 128.f) + SUBLN_EPS);
;                 const long tok = P.qtok(wid, crow(r, hi));
; #pragma unroll
;                 for (int d = 0; d < NB; ++d) X.att[tok * D + P.h * 128 + d * 32 + r32] = (bf16_t)(cvtpk(o[d][r] * rs * X.subln[d * 32 + r32], 0.f) & 0xffffu); }
;         }
	v_add_f32_e32 v4, v4, v5
	v_fmamk_f32 v4, v4, 0x3c000000, v157
	v_cmp_gt_f32_e32 vcc, s2, v4
	v_mul_f32_e32 v5, 0x4f800000, v4
	s_nop 0
	v_cndmask_b32_e32 v4, v4, v5, vcc
	v_sqrt_f32_e32 v5, v4
	s_nop 0
	v_add_u32_e32 v82, -1, v5
	v_fma_f32 v85, -v82, v5, v4
	v_cmp_ge_f32_e64 s[4:5], 0, v85
	v_add_u32_e32 v85, 1, v5
	s_nop 0
	v_cndmask_b32_e64 v82, v5, v82, s[4:5]
	v_fma_f32 v5, -v85, v5, v4
	v_cmp_lt_f32_e64 s[4:5], 0, v5
	s_nop 1
	v_cndmask_b32_e64 v5, v82, v85, s[4:5]
	v_mul_f32_e32 v82, 0x37800000, v5
	v_cndmask_b32_e32 v5, v5, v82, vcc
	v_cmp_class_f32_e32 vcc, v4, v216
	s_nop 1
	v_cndmask_b32_e32 v4, v5, v4, vcc
	v_div_scale_f32 v5, s[0:1], v4, v4, s3
	v_rcp_f32_e32 v82, v5
	s_nop 0
	v_fma_f32 v85, -v5, v82, 1.0
	v_fmac_f32_e32 v82, v85, v82
	v_div_scale_f32 v85, vcc, s3, v4, s3
	v_mul_f32_e32 v86, v85, v82
	v_fma_f32 v87, -v5, v86, v85
	v_fmac_f32_e32 v86, v87, v82
	v_fma_f32 v5, -v5, v86, v85
	v_div_fmas_f32 v5, v5, v82, v86
	v_div_fixup_f32 v82, v5, v4, s3
	v_lshlrev_b64 v[4:5], 11, v[2:3]
	v_mul_f32_e32 v2, v83, v82
	v_mov_b32_e32 v83, v192
	v_lshl_add_u64 v[4:5], s[90:91], 0, v[4:5]
	v_lshl_add_u64 v[4:5], v[4:5], 0, s[26:27]
	v_lshl_add_u64 v[4:5], v[4:5], 0, v[0:1]
	s_nop 0
	v_mul_f32_e32 v2, v83, v2
	v_cvt_pk_bf16_f32 v2, v2, v1
	v_mov_b32_e32 v83, v193
	s_nop 0
	global_store_short v[4:5], v2, off
	v_mul_f32_e32 v2, v84, v82
	s_nop 0
	v_mul_f32_e32 v2, v83, v2
	v_cvt_pk_bf16_f32 v2, v2, v1
	global_store_short v[4:5], v2, off offset:64
	v_mul_f32_e32 v2, v81, v82
	v_mov_b32_e32 v81, v194
	s_nop 0
	v_mul_f32_e32 v2, v81, v2
	v_cvt_pk_bf16_f32 v2, v2, v1
	global_store_short v[4:5], v2, off offset:128
	v_mul_f32_e32 v2, v80, v82
	v_mov_b32_e32 v80, v195
	s_nop 0
	v_mul_f32_e32 v2, v2, v80
	v_cvt_pk_bf16_f32 v2, v2, v1
	global_store_short v[4:5], v2, off offset:192
	v_or_b32_e32 v2, 19, v227
	v_lshl_add_u32 v80, v2, 9, v13
	ds_read2_b32 v[4:5], v80 offset1:32
	v_or_b32_e32 v2, s21, v2
	v_or_b32_e32 v2, s8, v2
	s_waitcnt lgkmcnt(0)
	v_fma_f32 v83, v123, v145, -v4
	v_fma_f32 v84, v139, v145, -v5
	ds_read2_b32 v[4:5], v80 offset0:64 offset1:96
	v_mul_f32_e32 v82, v84, v84
	v_fmac_f32_e32 v82, v83, v83
	s_waitcnt lgkmcnt(0)
	v_fma_f32 v81, v107, v145, -v4
	v_fmac_f32_e32 v82, v81, v81
	v_fma_f32 v80, v91, v145, -v5
	v_fmac_f32_e32 v82, v80, v80
	ds_bpermute_b32 v4, v12, v82
	s_waitcnt lgkmcnt(0)
	v_add_f32_e32 v4, v82, v4
	ds_bpermute_b32 v5, v11, v4
	s_waitcnt lgkmcnt(0)
	v_add_f32_e32 v4, v4, v5
	ds_bpermute_b32 v5, v10, v4
	s_waitcnt lgkmcnt(0)
	v_add_f32_e32 v4, v4, v5
	ds_bpermute_b32 v5, v9, v4
	s_waitcnt lgkmcnt(0)
	v_add_f32_e32 v4, v4, v5
	ds_bpermute_b32 v5, v8, v4
	s_waitcnt lgkmcnt(0)
	v_add_f32_e32 v4, v4, v5
	v_fmamk_f32 v4, v4, 0x3c000000, v157
	v_cmp_gt_f32_e32 vcc, s2, v4
	v_mul_f32_e32 v5, 0x4f800000, v4
	s_nop 0
	v_cndmask_b32_e32 v4, v4, v5, vcc
	v_sqrt_f32_e32 v5, v4
	s_nop 0
	v_add_u32_e32 v82, -1, v5
	v_fma_f32 v85, -v82, v5, v4
	v_cmp_ge_f32_e64 s[4:5], 0, v85
	v_add_u32_e32 v85, 1, v5
	s_nop 0
	v_cndmask_b32_e64 v82, v5, v82, s[4:5]
	v_fma_f32 v5, -v85, v5, v4
	v_cmp_lt_f32_e64 s[4:5], 0, v5
	s_nop 1
	v_cndmask_b32_e64 v5, v82, v85, s[4:5]
	v_mul_f32_e32 v82, 0x37800000, v5
	v_cndmask_b32_e32 v5, v5, v82, vcc
	v_cmp_class_f32_e32 vcc, v4, v216
	s_nop 1
	v_cndmask_b32_e32 v4, v5, v4, vcc
	v_div_scale_f32 v5, s[0:1], v4, v4, s3
	v_rcp_f32_e32 v82, v5
	s_nop 0
	v_fma_f32 v85, -v5, v82, 1.0
	v_fmac_f32_e32 v82, v85, v82
	v_div_scale_f32 v85, vcc, s3, v4, s3
	v_mul_f32_e32 v86, v85, v82
	v_fma_f32 v87, -v5, v86, v85
	v_fmac_f32_e32 v86, v87, v82
	v_fma_f32 v5, -v5, v86, v85
	v_div_fmas_f32 v5, v5, v82, v86
	v_div_fixup_f32 v82, v5, v4, s3
	v_lshlrev_b64 v[4:5], 11, v[2:3]
	v_mul_f32_e32 v2, v83, v82
	v_mov_b32_e32 v83, v192
	v_lshl_add_u64 v[4:5], s[90:91], 0, v[4:5]
	v_lshl_add_u64 v[4:5], v[4:5], 0, s[26:27]
	v_lshl_add_u64 v[4:5], v[4:5], 0, v[0:1]
	s_nop 0
	v_mul_f32_e32 v2, v83, v2
	v_cvt_pk_bf16_f32 v2, v2, v1
	v_mov_b32_e32 v83, v193
	s_nop 0
	global_store_short v[4:5], v2, off
	v_mul_f32_e32 v2, v84, v82
	s_nop 0
	v_mul_f32_e32 v2, v83, v2
	v_cvt_pk_bf16_f32 v2, v2, v1
	global_store_short v[4:5], v2, off offset:64
	v_mul_f32_e32 v2, v81, v82
	v_mov_b32_e32 v81, v194
	s_nop 0
	v_mul_f32_e32 v2, v81, v2
	v_cvt_pk_bf16_f32 v2, v2, v1
	global_store_short v[4:5], v2, off offset:128
	v_mul_f32_e32 v2, v80, v82
	v_mov_b32_e32 v80, v195
	s_nop 0
	v_mul_f32_e32 v2, v2, v80
	v_cvt_pk_bf16_f32 v2, v2, v1
	global_store_short v[4:5], v2, off offset:192
	v_or_b32_e32 v2, 24, v227
	v_lshl_add_u32 v80, v2, 9, v13
	ds_read2_b32 v[4:5], v80 offset1:32
	v_or_b32_e32 v2, s21, v2
	v_or_b32_e32 v2, s8, v2
	s_waitcnt lgkmcnt(0)
	v_fma_f32 v83, v124, v144, -v4
	v_fma_f32 v84, v140, v144, -v5
	ds_read2_b32 v[4:5], v80 offset0:64 offset1:96
	v_mul_f32_e32 v82, v84, v84
	v_fmac_f32_e32 v82, v83, v83
	s_waitcnt lgkmcnt(0)
	v_fma_f32 v81, v108, v144, -v4
	v_fmac_f32_e32 v82, v81, v81
	v_fma_f32 v80, v92, v144, -v5
	v_fmac_f32_e32 v82, v80, v80
	ds_bpermute_b32 v4, v12, v82
	s_waitcnt lgkmcnt(0)
	v_add_f32_e32 v4, v82, v4
	ds_bpermute_b32 v5, v11, v4
	s_waitcnt lgkmcnt(0)
	v_add_f32_e32 v4, v4, v5
	ds_bpermute_b32 v5, v10, v4
	s_waitcnt lgkmcnt(0)
	v_add_f32_e32 v4, v4, v5
	ds_bpermute_b32 v5, v9, v4
	s_waitcnt lgkmcnt(0)
	v_add_f32_e32 v4, v4, v5
	ds_bpermute_b32 v5, v8, v4
	s_waitcnt lgkmcnt(0)
; __device__ __forceinline__ unsigned cvtpk(float lo, float hi) { unsigned r; asm volatile("v_cvt_pk_bf16_f32 %0, %1, %2" : "=v"(r) : "v"(lo), "v"(hi)); return r; }
; __device__ __forceinline__ float sx(float v, int mask, int lane) { return __int_as_float(__builtin_amdgcn_ds_bpermute((lane ^ mask) << 2, __float_as_int(v))); }
; __device__ __forceinline__ int crow(int r, int hi) { return (r & 3) + 8 * (r >> 2) + 4 * hi; }
;     __device__ __forceinline__ long qtok(int wid, int i) const { return (long)b * T + res + dil * (qs0 + 32 * wid + i); }
;     __device__ __forceinline__ long qtok(int wid, int i) const { return (long)b * T + 256 * qb + 32 * wid + i; }
;     __device__ __forceinline__ long qtok(int wid, int i) const { return (long)b * T + 128 * qb + 32 * (wid & 3) + i; }
; template <class Pol>
; __device__ __forceinline__ void attn_unit(const Pol& P, LAS unsigned char* lds, const Ptrs& X, bf16x8& pq0, bf16x8& pq1, bf16x8& pq2, bf16x8& pq3, bf16x8& pk_, bf16x8& pv_, bool have, const Pol& Pn, bool hasn) {
;     ...
;         if (wid < 4) {
; #pragma unroll
;             for (int r = 0; r < 16; ++r) { const int row = 32 * wid + crow(r, hi); float s = 0.f;
; #pragma unroll
;                 for (int d = 0; d < NB; ++d) { const float y = o[d][r] * rli[r] - XB[row * 128 + d * 32 + r32]; o[d][r] = y; s += y * y; }
;                 s += sx(s, 1, lane); s += sx(s, 2, lane); s += sx(s, 4, lane); s += sx(s, 8, lane); s += sx(s, 16, lane);
;                 const float rs = (1.0f - LAM_INIT) / sqrtf(s * (1.0f / 128.f) + SUBLN_EPS);
;                 const long tok = P.qtok(wid, crow(r, hi));
; #pragma unroll
;                 for (int d = 0; d < NB; ++d) X.att[tok * D + P.h * 128 + d * 32 + r32] = (bf16_t)(cvtpk(o[d][r] * rs * X.subln[d * 32 + r32], 0.f) & 0xffffu); }
;         }
	v_add_f32_e32 v4, v4, v5
	v_fmamk_f32 v4, v4, 0x3c000000, v157
	v_cmp_gt_f32_e32 vcc, s2, v4
	v_mul_f32_e32 v5, 0x4f800000, v4
	s_nop 0
	v_cndmask_b32_e32 v4, v4, v5, vcc
	v_sqrt_f32_e32 v5, v4
	s_nop 0
	v_add_u32_e32 v82, -1, v5
	v_fma_f32 v85, -v82, v5, v4
	v_cmp_ge_f32_e64 s[4:5], 0, v85
	v_add_u32_e32 v85, 1, v5
	s_nop 0
	v_cndmask_b32_e64 v82, v5, v82, s[4:5]
	v_fma_f32 v5, -v85, v5, v4
	v_cmp_lt_f32_e64 s[4:5], 0, v5
	s_nop 1
	v_cndmask_b32_e64 v5, v82, v85, s[4:5]
	v_mul_f32_e32 v82, 0x37800000, v5
	v_cndmask_b32_e32 v5, v5, v82, vcc
	v_cmp_class_f32_e32 vcc, v4, v216
	s_nop 1
	v_cndmask_b32_e32 v4, v5, v4, vcc
	v_div_scale_f32 v5, s[0:1], v4, v4, s3
	v_rcp_f32_e32 v82, v5
	s_nop 0
	v_fma_f32 v85, -v5, v82, 1.0
	v_fmac_f32_e32 v82, v85, v82
	v_div_scale_f32 v85, vcc, s3, v4, s3
	v_mul_f32_e32 v86, v85, v82
	v_fma_f32 v87, -v5, v86, v85
	v_fmac_f32_e32 v86, v87, v82
	v_fma_f32 v5, -v5, v86, v85
	v_div_fmas_f32 v5, v5, v82, v86
	v_div_fixup_f32 v82, v5, v4, s3
	v_lshlrev_b64 v[4:5], 11, v[2:3]
	v_mul_f32_e32 v2, v83, v82
	v_mov_b32_e32 v83, v192
	v_lshl_add_u64 v[4:5], s[90:91], 0, v[4:5]
	v_lshl_add_u64 v[4:5], v[4:5], 0, s[26:27]
	v_lshl_add_u64 v[4:5], v[4:5], 0, v[0:1]
	s_nop 0
	v_mul_f32_e32 v2, v83, v2
	v_cvt_pk_bf16_f32 v2, v2, v1
	v_mov_b32_e32 v83, v193
	s_nop 0
	global_store_short v[4:5], v2, off
	v_mul_f32_e32 v2, v84, v82
	s_nop 0
	v_mul_f32_e32 v2, v83, v2
	v_cvt_pk_bf16_f32 v2, v2, v1
	global_store_short v[4:5], v2, off offset:64
	v_mul_f32_e32 v2, v81, v82
	v_mov_b32_e32 v81, v194
	s_nop 0
	v_mul_f32_e32 v2, v81, v2
	v_cvt_pk_bf16_f32 v2, v2, v1
	global_store_short v[4:5], v2, off offset:128
	v_mul_f32_e32 v2, v80, v82
	v_mov_b32_e32 v80, v195
	s_nop 0
	v_mul_f32_e32 v2, v2, v80
	v_cvt_pk_bf16_f32 v2, v2, v1
	global_store_short v[4:5], v2, off offset:192
	v_or_b32_e32 v2, 25, v227
	v_lshl_add_u32 v80, v2, 9, v13
	ds_read2_b32 v[4:5], v80 offset1:32
	v_or_b32_e32 v2, s21, v2
	v_or_b32_e32 v2, s8, v2
	s_waitcnt lgkmcnt(0)
	v_fma_f32 v82, v125, v15, -v4
	v_fma_f32 v83, v141, v15, -v5
	ds_read2_b32 v[4:5], v80 offset0:64 offset1:96
	v_mul_f32_e32 v81, v83, v83
	v_fmac_f32_e32 v81, v82, v82
	s_waitcnt lgkmcnt(0)
	v_fma_f32 v80, v109, v15, -v4
	v_fmac_f32_e32 v81, v80, v80
	v_fma_f32 v15, v93, v15, -v5
	v_fmac_f32_e32 v81, v15, v15
	ds_bpermute_b32 v4, v12, v81
	s_waitcnt lgkmcnt(0)
	v_add_f32_e32 v4, v81, v4
	ds_bpermute_b32 v5, v11, v4
	s_waitcnt lgkmcnt(0)
	v_add_f32_e32 v4, v4, v5
	ds_bpermute_b32 v5, v10, v4
	s_waitcnt lgkmcnt(0)
	v_add_f32_e32 v4, v4, v5
	ds_bpermute_b32 v5, v9, v4
	s_waitcnt lgkmcnt(0)
	v_add_f32_e32 v4, v4, v5
	ds_bpermute_b32 v5, v8, v4
	s_waitcnt lgkmcnt(0)
	v_add_f32_e32 v4, v4, v5
	v_fmamk_f32 v4, v4, 0x3c000000, v157
	v_cmp_gt_f32_e32 vcc, s2, v4
	v_mul_f32_e32 v5, 0x4f800000, v4
	s_nop 0
	v_cndmask_b32_e32 v4, v4, v5, vcc
	v_sqrt_f32_e32 v5, v4
	s_nop 0
	v_add_u32_e32 v81, -1, v5
	v_fma_f32 v84, -v81, v5, v4
	v_cmp_ge_f32_e64 s[4:5], 0, v84
	v_add_u32_e32 v84, 1, v5
	s_nop 0
	v_cndmask_b32_e64 v81, v5, v81, s[4:5]
	v_fma_f32 v5, -v84, v5, v4
	v_cmp_lt_f32_e64 s[4:5], 0, v5
	s_nop 1
	v_cndmask_b32_e64 v5, v81, v84, s[4:5]
	v_mul_f32_e32 v81, 0x37800000, v5
	v_cndmask_b32_e32 v5, v5, v81, vcc
	v_cmp_class_f32_e32 vcc, v4, v216
	s_nop 1
	v_cndmask_b32_e32 v4, v5, v4, vcc
	v_div_scale_f32 v5, s[0:1], v4, v4, s3
	v_rcp_f32_e32 v81, v5
	s_nop 0
	v_fma_f32 v84, -v5, v81, 1.0
	v_fmac_f32_e32 v81, v84, v81
	v_div_scale_f32 v84, vcc, s3, v4, s3
	v_mul_f32_e32 v85, v84, v81
	v_fma_f32 v86, -v5, v85, v84
	v_fmac_f32_e32 v85, v86, v81
	v_fma_f32 v5, -v5, v85, v84
	v_div_fmas_f32 v5, v5, v81, v85
	v_div_fixup_f32 v81, v5, v4, s3
	v_lshlrev_b64 v[4:5], 11, v[2:3]
	v_mul_f32_e32 v2, v82, v81
	v_mov_b32_e32 v82, v192
	v_lshl_add_u64 v[4:5], s[90:91], 0, v[4:5]
	v_lshl_add_u64 v[4:5], v[4:5], 0, s[26:27]
	v_lshl_add_u64 v[4:5], v[4:5], 0, v[0:1]
	s_nop 0
	v_mul_f32_e32 v2, v82, v2
	v_cvt_pk_bf16_f32 v2, v2, v1
	v_mov_b32_e32 v82, v193
	s_nop 0
	global_store_short v[4:5], v2, off
	v_mul_f32_e32 v2, v83, v81
	s_nop 0
	v_mul_f32_e32 v2, v82, v2
	v_cvt_pk_bf16_f32 v2, v2, v1
	global_store_short v[4:5], v2, off offset:64
	v_mul_f32_e32 v2, v80, v81
	v_mov_b32_e32 v80, v194
	s_nop 0
	v_mul_f32_e32 v2, v80, v2
	v_cvt_pk_bf16_f32 v2, v2, v1
	global_store_short v[4:5], v2, off offset:128
	v_mul_f32_e32 v2, v15, v81
	v_mov_b32_e32 v15, v195
	s_nop 0
	v_mul_f32_e32 v2, v2, v15
	v_cvt_pk_bf16_f32 v2, v2, v1
	global_store_short v[4:5], v2, off offset:192
	v_or_b32_e32 v2, 26, v227
	v_lshl_add_u32 v15, v2, 9, v13
	ds_read2_b32 v[4:5], v15 offset1:32
	v_or_b32_e32 v2, s21, v2
	v_or_b32_e32 v2, s8, v2
	s_waitcnt lgkmcnt(0)
	v_fma_f32 v81, v126, v14, -v4
	v_fma_f32 v82, v142, v14, -v5
	ds_read2_b32 v[4:5], v15 offset0:64 offset1:96
	v_mul_f32_e32 v80, v82, v82
	v_fmac_f32_e32 v80, v81, v81
	s_waitcnt lgkmcnt(0)
; __device__ __forceinline__ unsigned cvtpk(float lo, float hi) { unsigned r; asm volatile("v_cvt_pk_bf16_f32 %0, %1, %2" : "=v"(r) : "v"(lo), "v"(hi)); return r; }
; __device__ __forceinline__ float sx(float v, int mask, int lane) { return __int_as_float(__builtin_amdgcn_ds_bpermute((lane ^ mask) << 2, __float_as_int(v))); }
; __device__ __forceinline__ int crow(int r, int hi) { return (r & 3) + 8 * (r >> 2) + 4 * hi; }
;     __device__ __forceinline__ long qtok(int wid, int i) const { return (long)b * T + res + dil * (qs0 + 32 * wid + i); }
;     __device__ __forceinline__ long qtok(int wid, int i) const { return (long)b * T + 256 * qb + 32 * wid + i; }
;     __device__ __forceinline__ long qtok(int wid, int i) const { return (long)b * T + 128 * qb + 32 * (wid & 3) + i; }
; template <class Pol>
; __device__ __forceinline__ void attn_unit(const Pol& P, LAS unsigned char* lds, const Ptrs& X, bf16x8& pq0, bf16x8& pq1, bf16x8& pq2, bf16x8& pq3, bf16x8& pk_, bf16x8& pv_, bool have, const Pol& Pn, bool hasn) {
;     ...
;         if (wid < 4) {
; #pragma unroll
;             for (int r = 0; r < 16; ++r) { const int row = 32 * wid + crow(r, hi); float s = 0.f;
; #pragma unroll
;                 for (int d = 0; d < NB; ++d) { const float y = o[d][r] * rli[r] - XB[row * 128 + d * 32 + r32]; o[d][r] = y; s += y * y; }
;                 s += sx(s, 1, lane); s += sx(s, 2, lane); s += sx(s, 4, lane); s += sx(s, 8, lane); s += sx(s, 16, lane);
;                 const float rs = (1.0f - LAM_INIT) / sqrtf(s * (1.0f / 128.f) + SUBLN_EPS);
;                 const long tok = P.qtok(wid, crow(r, hi));
; #pragma unroll
;                 for (int d = 0; d < NB; ++d) X.att[tok * D + P.h * 128 + d * 32 + r32] = (bf16_t)(cvtpk(o[d][r] * rs * X.subln[d * 32 + r32], 0.f) & 0xffffu); }
;         }
	v_fma_f32 v15, v110, v14, -v4
	v_fmac_f32_e32 v80, v15, v15
	v_fma_f32 v14, v94, v14, -v5
	v_fmac_f32_e32 v80, v14, v14
	ds_bpermute_b32 v4, v12, v80
	s_waitcnt lgkmcnt(0)
	v_add_f32_e32 v4, v80, v4
	ds_bpermute_b32 v5, v11, v4
	s_waitcnt lgkmcnt(0)
	v_add_f32_e32 v4, v4, v5
	ds_bpermute_b32 v5, v10, v4
	s_waitcnt lgkmcnt(0)
	v_add_f32_e32 v4, v4, v5
	ds_bpermute_b32 v5, v9, v4
	s_waitcnt lgkmcnt(0)
	v_add_f32_e32 v4, v4, v5
	ds_bpermute_b32 v5, v8, v4
	s_waitcnt lgkmcnt(0)
	v_add_f32_e32 v4, v4, v5
	v_fmamk_f32 v4, v4, 0x3c000000, v157
	v_cmp_gt_f32_e32 vcc, s2, v4
	v_mul_f32_e32 v5, 0x4f800000, v4
	s_nop 0
	v_cndmask_b32_e32 v4, v4, v5, vcc
	v_sqrt_f32_e32 v5, v4
	s_nop 0
	v_add_u32_e32 v80, -1, v5
	v_fma_f32 v83, -v80, v5, v4
	v_cmp_ge_f32_e64 s[4:5], 0, v83
	v_add_u32_e32 v83, 1, v5
	s_nop 0
	v_cndmask_b32_e64 v80, v5, v80, s[4:5]
	v_fma_f32 v5, -v83, v5, v4
	v_cmp_lt_f32_e64 s[4:5], 0, v5
	s_nop 1
	v_cndmask_b32_e64 v5, v80, v83, s[4:5]
	v_mul_f32_e32 v80, 0x37800000, v5
	v_cndmask_b32_e32 v5, v5, v80, vcc
	v_cmp_class_f32_e32 vcc, v4, v216
	s_nop 1
	v_cndmask_b32_e32 v4, v5, v4, vcc
	v_div_scale_f32 v5, s[0:1], v4, v4, s3
	v_rcp_f32_e32 v80, v5
	s_nop 0
	v_fma_f32 v83, -v5, v80, 1.0
	v_fmac_f32_e32 v80, v83, v80
	v_div_scale_f32 v83, vcc, s3, v4, s3
	v_mul_f32_e32 v84, v83, v80
	v_fma_f32 v85, -v5, v84, v83
	v_fmac_f32_e32 v84, v85, v80
	v_fma_f32 v5, -v5, v84, v83
	v_div_fmas_f32 v5, v5, v80, v84
	v_div_fixup_f32 v80, v5, v4, s3
	v_lshlrev_b64 v[4:5], 11, v[2:3]
	v_mul_f32_e32 v2, v81, v80
	v_mov_b32_e32 v81, v192
	v_lshl_add_u64 v[4:5], s[90:91], 0, v[4:5]
	v_lshl_add_u64 v[4:5], v[4:5], 0, s[26:27]
	v_lshl_add_u64 v[4:5], v[4:5], 0, v[0:1]
	s_nop 0
	v_mul_f32_e32 v2, v81, v2
	v_cvt_pk_bf16_f32 v2, v2, v1
	v_mov_b32_e32 v81, v193
	s_nop 0
	global_store_short v[4:5], v2, off
	v_mul_f32_e32 v2, v82, v80
	s_nop 0
	v_mul_f32_e32 v2, v81, v2
	v_cvt_pk_bf16_f32 v2, v2, v1
	global_store_short v[4:5], v2, off offset:64
	v_mul_f32_e32 v2, v15, v80
	v_mov_b32_e32 v15, v194
	s_nop 0
	v_mul_f32_e32 v2, v15, v2
	v_cvt_pk_bf16_f32 v2, v2, v1
	global_store_short v[4:5], v2, off offset:128
	v_mul_f32_e32 v2, v14, v80
	v_mov_b32_e32 v14, v195
	s_nop 0
	v_mul_f32_e32 v2, v2, v14
	v_cvt_pk_bf16_f32 v2, v2, v1
	global_store_short v[4:5], v2, off offset:192
	v_or_b32_e32 v2, 27, v227
	v_lshl_add_u32 v13, v2, 9, v13
	ds_read2_b32 v[4:5], v13 offset1:32
	ds_read2_b32 v[14:15], v13 offset0:64 offset1:96
	v_or_b32_e32 v2, s21, v2
	v_or_b32_e32 v2, s8, v2
	v_lshlrev_b64 v[2:3], 11, v[2:3]
	s_waitcnt lgkmcnt(1)
	v_fma_f32 v81, v143, v7, -v5
	v_fma_f32 v80, v127, v7, -v4
	v_mul_f32_e32 v82, v81, v81
	v_fmac_f32_e32 v82, v80, v80
	s_waitcnt lgkmcnt(0)
	v_fma_f32 v5, v111, v7, -v14
	v_fmac_f32_e32 v82, v5, v5
	v_fma_f32 v4, v95, v7, -v15
	v_fmac_f32_e32 v82, v4, v4
	ds_bpermute_b32 v7, v12, v82
	v_lshl_add_u64 v[2:3], s[90:91], 0, v[2:3]
	v_lshl_add_u64 v[2:3], v[2:3], 0, s[26:27]
	v_lshl_add_u64 v[2:3], v[2:3], 0, v[0:1]
	s_waitcnt lgkmcnt(0)
	v_add_f32_e32 v7, v82, v7
	ds_bpermute_b32 v11, v11, v7
	s_waitcnt lgkmcnt(0)
	v_add_f32_e32 v7, v7, v11
	ds_bpermute_b32 v10, v10, v7
	s_waitcnt lgkmcnt(0)
	v_add_f32_e32 v7, v7, v10
	ds_bpermute_b32 v9, v9, v7
	s_waitcnt lgkmcnt(0)
	v_add_f32_e32 v7, v7, v9
	ds_bpermute_b32 v8, v8, v7
	s_waitcnt lgkmcnt(0)
	v_add_f32_e32 v7, v7, v8
	v_fmamk_f32 v7, v7, 0x3c000000, v157
	v_cmp_gt_f32_e32 vcc, s2, v7
	v_mul_f32_e32 v8, 0x4f800000, v7
	s_nop 0
	v_cndmask_b32_e32 v7, v7, v8, vcc
	v_sqrt_f32_e32 v8, v7
	s_nop 0
	v_add_u32_e32 v9, -1, v8
	v_fma_f32 v10, -v9, v8, v7
	v_cmp_ge_f32_e64 s[4:5], 0, v10
	v_add_u32_e32 v10, 1, v8
	s_nop 0
	v_cndmask_b32_e64 v9, v8, v9, s[4:5]
	v_fma_f32 v8, -v10, v8, v7
	v_cmp_lt_f32_e64 s[4:5], 0, v8
	s_nop 1
	v_cndmask_b32_e64 v8, v9, v10, s[4:5]
	v_mul_f32_e32 v9, 0x37800000, v8
	v_cndmask_b32_e32 v8, v8, v9, vcc
	v_cmp_class_f32_e32 vcc, v7, v216
	s_nop 1
	v_cndmask_b32_e32 v7, v8, v7, vcc
	v_div_scale_f32 v8, s[0:1], v7, v7, s3
	v_rcp_f32_e32 v9, v8
	s_nop 0
	v_fma_f32 v10, -v8, v9, 1.0
	v_fmac_f32_e32 v9, v10, v9
	v_div_scale_f32 v10, vcc, s3, v7, s3
	v_mul_f32_e32 v11, v10, v9
	v_fma_f32 v12, -v8, v11, v10
	v_fmac_f32_e32 v11, v12, v9
	v_fma_f32 v8, -v8, v11, v10
	v_div_fmas_f32 v8, v8, v9, v11
	v_mov_b32_e32 v9, v192
	v_div_fixup_f32 v7, v8, v7, s3
	v_mul_f32_e32 v8, v80, v7
	v_mul_f32_e32 v0, v81, v7
	s_nop 0
	v_mul_f32_e32 v8, v9, v8
	v_cvt_pk_bf16_f32 v8, v8, v1
	global_store_short v[2:3], v8, off
	v_mov_b32_e32 v8, v193
	s_nop 0
	v_mul_f32_e32 v0, v8, v0
	v_cvt_pk_bf16_f32 v0, v0, v1
	global_store_short v[2:3], v0, off offset:64
	v_mul_f32_e32 v0, v5, v7
	v_mov_b32_e32 v5, v194
	s_nop 0
	v_mul_f32_e32 v0, v5, v0
	v_cvt_pk_bf16_f32 v0, v0, v1
	global_store_short v[2:3], v0, off offset:128
	v_mul_f32_e32 v0, v4, v7
	v_mov_b32_e32 v4, v195
	s_nop 0
	v_mul_f32_e32 v0, v0, v4
	v_cvt_pk_bf16_f32 v0, v0, v1
	global_store_short v[2:3], v0, off offset:192
